# attention: prompt-unit Q loads issued with the K/V staging loads; NA-row Q loads issued before the previous row's key-window slide
# speedup vs baseline: 1.0236x; 1.0013x over previous
.LBB0_106:
	s_ashr_i32 s0, s2, 4
	s_ashr_i32 s1, s0, 31
	s_lshl_b32 s3, s2, 6
	s_and_b32 s26, s3, 0x3c0
	s_lshl_b64 s[0:1], s[0:1], 19
	s_barrier
	s_and_saveexec_b64 s[20:21], s[38:39]
	s_movk_i32 s33, 0x5ff
	s_cbranch_execz .LBB0_111
	v_readlane_b32 s22, v253, 4
	v_readlane_b32 s23, v253, 5
	s_add_u32 s3, s22, s0
	s_addc_u32 s23, s23, s1
	s_lshl_b32 s22, s26, 1
	s_add_u32 s22, s3, s22
	s_addc_u32 s23, s23, 0
	v_lshl_add_u64 v[0:1], s[22:23], 0, v[178:179]
	v_mov_b32_e32 v2, v192
	v_ashrrev_i32_e32 v8, 3, v2
	v_ashrrev_i32_e32 v9, 31, v8
	v_lshlrev_b64 v[4:5], 11, v[8:9]
	v_lshl_add_u64 v[4:5], v[0:1], 0, v[4:5]
	global_load_dwordx4 v[16:19], v[4:5], off
	v_mad_u64_u32 v[48:49], s[34:35], v8, s43, v[90:91]
	v_add_u32_e32 v2, 0x200, v192
	v_ashrrev_i32_e32 v8, 3, v2
	v_ashrrev_i32_e32 v9, 31, v8
	v_lshlrev_b64 v[4:5], 11, v[8:9]
	v_lshl_add_u64 v[4:5], v[0:1], 0, v[4:5]
	global_load_dwordx4 v[20:23], v[4:5], off
	v_mad_u64_u32 v[50:51], s[34:35], v8, s43, v[90:91]
	v_add_u32_e32 v2, 0x400, v192
	v_ashrrev_i32_e32 v8, 3, v2
	v_ashrrev_i32_e32 v9, 31, v8
	v_lshlrev_b64 v[4:5], 11, v[8:9]
	v_lshl_add_u64 v[4:5], v[0:1], 0, v[4:5]
	global_load_dwordx4 v[24:27], v[4:5], off
	v_mad_u64_u32 v[52:53], s[34:35], v8, s43, v[90:91]
	v_add_u32_e32 v2, 0x600, v192
	v_ashrrev_i32_e32 v8, 3, v2
	v_ashrrev_i32_e32 v9, 31, v8
	v_lshlrev_b64 v[4:5], 11, v[8:9]
	v_lshl_add_u64 v[4:5], v[0:1], 0, v[4:5]
	global_load_dwordx4 v[28:31], v[4:5], off
	v_mad_u64_u32 v[54:55], s[34:35], v8, s43, v[90:91]
	s_ashr_i32 s3, s2, 31
	s_lshl_b64 s[22:23], s[2:3], 15
	v_lshl_add_u64 v[0:1], v[92:93], 0, s[22:23]
	v_mov_b32_e32 v2, v192
	v_ashrrev_i32_e32 v8, 5, v2
	v_ashrrev_i32_e32 v9, 31, v8
	v_lshlrev_b64 v[4:5], 9, v[8:9]
	v_lshl_add_u64 v[4:5], v[0:1], 0, v[4:5]
	global_load_dwordx4 v[32:35], v[4:5], off
	v_mad_u64_u32 v[56:57], s[34:35], v8, s42, v[94:95]
	v_add_u32_e32 v2, 0x200, v192
	v_ashrrev_i32_e32 v8, 5, v2
	v_ashrrev_i32_e32 v9, 31, v8
	v_lshlrev_b64 v[4:5], 9, v[8:9]
	v_lshl_add_u64 v[4:5], v[0:1], 0, v[4:5]
	global_load_dwordx4 v[36:39], v[4:5], off
	v_mad_u64_u32 v[58:59], s[34:35], v8, s42, v[94:95]
	v_add_u32_e32 v2, 0x400, v192
	v_ashrrev_i32_e32 v8, 5, v2
	v_ashrrev_i32_e32 v9, 31, v8
	v_lshlrev_b64 v[4:5], 9, v[8:9]
	v_lshl_add_u64 v[4:5], v[0:1], 0, v[4:5]
	global_load_dwordx4 v[40:43], v[4:5], off
	v_mad_u64_u32 v[60:61], s[34:35], v8, s42, v[94:95]
	v_add_u32_e32 v2, 0x600, v192
	v_ashrrev_i32_e32 v8, 5, v2
	v_ashrrev_i32_e32 v9, 31, v8
	v_lshlrev_b64 v[4:5], 9, v[8:9]
	v_lshl_add_u64 v[4:5], v[0:1], 0, v[4:5]
	global_load_dwordx4 v[44:47], v[4:5], off
	v_mad_u64_u32 v[62:63], s[34:35], v8, s42, v[94:95]
	v_lshl_add_u64 v[102:103], s[0:1], 0, v[98:99]
	v_readlane_b32 s0, v253, 2
	v_readlane_b32 s1, v253, 3
	s_lshl_b32 s26, s26, 1
	v_mov_b32_e32 v101, v179
	v_lshl_add_u64 v[0:1], s[0:1], 0, v[102:103]
	v_lshl_add_u64 v[0:1], v[0:1], 0, s[26:27]
	v_lshl_add_u64 v[8:9], v[0:1], 0, v[100:101]
	v_add_co_u32_e32 v12, vcc, 0x8000, v8
	s_nop 1
	v_addc_co_u32_e32 v13, vcc, 0, v9, vcc
	global_load_dwordx4 v[0:3], v[8:9], off
	global_load_dwordx4 v[4:7], v[8:9], off offset:64
	s_nop 0
	global_load_dwordx4 v[8:11], v[12:13], off
	s_nop 0
	global_load_dwordx4 v[12:15], v[12:13], off offset:64
	s_waitcnt vmcnt(11)
	ds_write_b128 v48, v[16:19]
	s_waitcnt vmcnt(10)
	ds_write_b128 v50, v[20:23]
	s_waitcnt vmcnt(9)
	ds_write_b128 v52, v[24:27]
	s_waitcnt vmcnt(8)
	ds_write_b128 v54, v[28:31]
	s_waitcnt vmcnt(7)
	ds_write_b128 v56, v[32:35]
	s_waitcnt vmcnt(6)
	ds_write_b128 v58, v[36:39]
	s_waitcnt vmcnt(5)
	ds_write_b128 v60, v[40:43]
	s_waitcnt vmcnt(4)
	ds_write_b128 v62, v[44:47]
.LBB0_111:
	s_or_b64 exec, exec, s[20:21]
	s_waitcnt lgkmcnt(0)
	s_barrier
	v_mov_b32_e32 v16, 0
	s_mov_b32 s3, 0
	v_mov_b32_e32 v107, 0xf149f2ca
	s_mov_b64 s[0:1], -1
	v_mov_b32_e32 v106, 0xf149f2ca
	v_mov_b32_e32 v17, v16
	v_mov_b32_e32 v18, v16
	v_mov_b32_e32 v19, v16
	v_mov_b32_e32 v20, v16
	v_mov_b32_e32 v21, v16
	v_mov_b32_e32 v22, v16
	v_mov_b32_e32 v23, v16
	v_mov_b32_e32 v24, v16
	v_mov_b32_e32 v25, v16
	v_mov_b32_e32 v26, v16
	v_mov_b32_e32 v27, v16
	v_mov_b32_e32 v28, v16
	v_mov_b32_e32 v29, v16
	v_mov_b32_e32 v30, v16
	v_mov_b32_e32 v31, v16
	v_mov_b32_e32 v32, v16
	v_mov_b32_e32 v33, v16
	v_mov_b32_e32 v34, v16
	v_mov_b32_e32 v35, v16
	v_mov_b32_e32 v36, v16
	v_mov_b32_e32 v37, v16
	v_mov_b32_e32 v38, v16
	v_mov_b32_e32 v39, v16
	v_mov_b32_e32 v40, v16
	v_mov_b32_e32 v41, v16
	v_mov_b32_e32 v42, v16
	v_mov_b32_e32 v43, v16
	v_mov_b32_e32 v44, v16
	v_mov_b32_e32 v45, v16
	v_mov_b32_e32 v46, v16
	v_mov_b32_e32 v47, v16
	v_mov_b32_e32 v104, v16
	v_mov_b32_e32 v105, v16
	s_mov_b32 s20, 0xf149f2ca

.LBB0_118:
	s_ashr_i32 s2, s63, 6
	s_ashr_i32 s56, s63, 2
	s_ashr_i32 s3, s2, 31
	s_and_b32 s58, s56, 15
	s_lshl_b64 s[2:3], s[2:3], 10
	s_add_u32 s2, s2, 0x2000
	s_addc_u32 s3, s3, 0
	s_lshl_b64 s[20:21], s[2:3], 11
	v_readlane_b32 s22, v253, 4
	v_readlane_b32 s23, v253, 5
	s_add_u32 s20, s22, s20
	s_addc_u32 s21, s23, s21
	s_lshl_b32 s26, s58, 7
	s_add_u32 s34, s20, s26
	s_addc_u32 s35, s21, 0
	s_lshl_b32 s20, s63, 2
	s_and_b32 s22, s20, 12
	v_sub_u32_e64 v0, s22, 4 clamp
	v_lshlrev_b32_e32 v1, 6, v0
	v_add_u32_e32 v2, v1, v108
	v_ashrrev_i32_e32 v3, 31, v2
	v_lshl_add_u64 v[70:71], s[34:35], 0, v[178:179]
	v_lshlrev_b64 v[2:3], 11, v[2:3]
	v_lshl_add_u64 v[2:3], v[70:71], 0, v[2:3]
	s_barrier
	global_load_dwordx4 v[12:15], v[2:3], off
	v_and_b32_e32 v1, 0x100, v1
	s_ashr_i32 s57, s56, 31
	v_add_u32_e32 v6, v1, v108
	s_movk_i32 s59, 0x90
	s_lshl_b64 s[36:37], s[56:57], 17
	v_mad_u64_u32 v[80:81], s[34:35], v6, s59, v[110:111]
	v_lshl_add_u64 v[68:69], v[138:139], 0, s[36:37]
	s_max_u32 s21, s22, 4
	s_lshl_b32 s20, s21, 6
	v_lshl_add_u32 v146, v1, 1, v109
	s_add_i32 s34, s20, 0xffffff40
	s_and_b32 s23, s34, 0x140
	s_mov_b32 s35, s27
	v_mov_b32_e32 v145, s3
	v_lshl_add_u64 v[142:143], v[112:113], 0, s[26:27]
	s_mov_b64 s[0:1], s[90:91]
	v_readlane_b32 s80, v253, 46
	v_readlane_b32 s94, v253, 60
	v_readlane_b32 s95, v253, 61
	v_lshlrev_b32_e32 v97, 2, v122
	v_lshlrev_b32_e32 v95, 2, v126
	v_lshlrev_b32_e32 v93, 2, v124
	v_lshlrev_b32_e32 v98, 2, v118
	v_lshlrev_b32_e32 v92, 2, v128
	v_lshlrev_b32_e32 v99, 2, v114
	v_lshlrev_b32_e32 v96, 2, v116
	v_lshlrev_b32_e32 v94, 2, v120
	v_readlane_b32 s81, v253, 47
	v_readlane_b32 s82, v253, 48
	v_readlane_b32 s83, v253, 49
	v_readlane_b32 s84, v253, 50
	v_readlane_b32 s85, v253, 51
	v_readlane_b32 s86, v253, 52
	v_readlane_b32 s87, v253, 53
	v_readlane_b32 s88, v253, 54
	v_readlane_b32 s89, v253, 55
	v_readlane_b32 s90, v253, 56
	v_readlane_b32 s91, v253, 57
	v_readlane_b32 s92, v253, 58
	v_readlane_b32 s93, v253, 59
	v_lshlrev_b32_e32 v2, 7, v0
	v_mov_b32_e32 v3, v179
	v_lshl_add_u64 v[2:3], v[68:69], 0, v[2:3]
	global_load_dwordx4 v[16:19], v[2:3], off
	v_add_u32_e32 v2, s34, v108
	v_ashrrev_i32_e32 v3, 31, v2
	v_lshlrev_b64 v[2:3], 11, v[2:3]
	v_lshl_add_u64 v[2:3], v[70:71], 0, v[2:3]
	global_load_dwordx4 v[20:23], v[2:3], off
	v_add_u32_e32 v1, s23, v108
	v_mad_u64_u32 v[82:83], s[36:37], v1, s59, v[110:111]
	v_lshl_add_u32 v147, s23, 1, v109
	v_lshl_add_u64 v[2:3], s[34:35], 1, v[68:69]
	global_load_dwordx4 v[24:27], v[2:3], off
	s_add_i32 s34, s20, 0xffffff80
	s_and_b32 s23, s34, 0x180
	v_add_u32_e32 v2, s34, v108
	v_ashrrev_i32_e32 v3, 31, v2
	v_lshlrev_b64 v[2:3], 11, v[2:3]
	v_lshl_add_u64 v[2:3], v[70:71], 0, v[2:3]
	global_load_dwordx4 v[28:31], v[2:3], off
	v_add_u32_e32 v1, s23, v108
	v_mad_u64_u32 v[84:85], s[36:37], v1, s59, v[110:111]
	v_lshl_add_u32 v148, s23, 1, v109
	v_lshl_add_u64 v[2:3], s[34:35], 1, v[68:69]
	global_load_dwordx4 v[32:35], v[2:3], off
	s_sub_i32 s34, s20, 64
	s_and_b32 s23, s34, 0x1c0
	v_add_u32_e32 v2, s34, v108
	v_ashrrev_i32_e32 v3, 31, v2
	v_lshlrev_b64 v[2:3], 11, v[2:3]
	v_lshl_add_u64 v[2:3], v[70:71], 0, v[2:3]
	global_load_dwordx4 v[36:39], v[2:3], off
	v_add_u32_e32 v1, s23, v108
	v_mad_u64_u32 v[86:87], s[36:37], v1, s59, v[110:111]
	v_lshl_add_u32 v149, s23, 1, v109
	s_and_b32 s23, s20, 0x100
	v_lshl_add_u64 v[2:3], s[34:35], 1, v[68:69]
	global_load_dwordx4 v[40:43], v[2:3], off
	v_add_u32_e32 v2, s20, v108
	v_ashrrev_i32_e32 v3, 31, v2
	v_lshlrev_b64 v[2:3], 11, v[2:3]
	v_lshl_add_u64 v[2:3], v[70:71], 0, v[2:3]
	global_load_dwordx4 v[44:47], v[2:3], off
	v_add_u32_e32 v1, s23, v108
	v_mad_u64_u32 v[100:101], s[34:35], v1, s59, v[110:111]
	s_lshl_b32 s34, s21, 7
	s_mov_b32 s35, s27
	v_lshl_add_u32 v150, s23, 1, v109
	s_or_b32 s21, s20, 64
	v_lshl_add_u64 v[6:7], v[68:69], 0, s[34:35]
	global_load_dwordx4 v[48:51], v[6:7], off
	v_add_u32_e32 v2, s21, v108
	v_ashrrev_i32_e32 v3, 31, v2
	v_lshlrev_b64 v[2:3], 11, v[2:3]
	v_lshl_add_u64 v[2:3], v[70:71], 0, v[2:3]
	global_load_dwordx4 v[52:55], v[2:3], off
	s_and_b32 s21, s21, 0x140
	v_add_u32_e32 v1, s21, v108
	v_mad_u64_u32 v[102:103], s[34:35], v1, s59, v[110:111]
	v_lshl_add_u32 v151, s21, 1, v109
	s_or_b32 s21, s20, 0x80
	s_or_b32 s20, s20, 0xc0
	global_load_dwordx4 v[56:59], v[6:7], off offset:128
	v_add_u32_e32 v2, s21, v108
	v_ashrrev_i32_e32 v3, 31, v2
	v_lshlrev_b64 v[2:3], 11, v[2:3]
	v_lshl_add_u64 v[2:3], v[70:71], 0, v[2:3]
	global_load_dwordx4 v[60:63], v[2:3], off
	s_and_b32 s21, s21, 0x180
	v_add_u32_e32 v1, s21, v108
	v_mad_u64_u32 v[104:105], s[34:35], v1, s59, v[110:111]
	v_lshl_add_u32 v152, s21, 1, v109
	global_load_dwordx4 v[64:67], v[6:7], off offset:256
	v_add_u32_e32 v2, s20, v108
	v_ashrrev_i32_e32 v3, 31, v2
	v_lshlrev_b64 v[2:3], 11, v[2:3]
	v_lshl_add_u64 v[2:3], v[70:71], 0, v[2:3]
	global_load_dwordx4 v[72:75], v[2:3], off
	s_and_b32 s20, s20, 0x1c0
	v_add_u32_e32 v1, s20, v108
	v_mad_u64_u32 v[106:107], s[34:35], v1, s59, v[110:111]
	v_lshl_add_u32 v153, s20, 1, v109
	s_mul_i32 s20, s58, 0x744
	s_add_u32 s36, s94, s20
	v_readfirstlane_b32 s20, v0
	s_addc_u32 s23, s95, 0
	s_add_i32 s20, s20, s61
	s_sub_i32 s21, s20, s22
	s_lshl_b32 s20, s20, 6
	s_and_b32 s35, s20, 0x100
	v_or_b32_e32 v0, s35, v115
	s_or_b32 s34, s35, 64
	s_or_b32 s33, s35, 0x80
	s_or_b32 s26, s35, 0xc0
	s_mul_i32 s20, s21, 31
	s_ashr_i32 s21, s20, 31
	s_lshl_b64 s[20:21], s[20:21], 2
	s_add_u32 s20, s36, s20
	s_addc_u32 s21, s23, s21
	global_load_dwordx4 v[76:79], v[6:7], off offset:384
	s_waitcnt vmcnt(15)
	ds_write_b128 v80, v[12:15]
	s_waitcnt vmcnt(14)
	ds_write_b128 v146, v[16:19]
	s_waitcnt vmcnt(13)
	ds_write_b128 v82, v[20:23]
	s_waitcnt vmcnt(12)
	ds_write_b128 v147, v[24:27]
	s_waitcnt vmcnt(11)
	ds_write_b128 v84, v[28:31]
	s_waitcnt vmcnt(10)
	ds_write_b128 v148, v[32:35]
	s_waitcnt vmcnt(9)
	ds_write_b128 v86, v[36:39]
	s_waitcnt vmcnt(8)
	ds_write_b128 v149, v[40:43]
	s_waitcnt vmcnt(7)
	ds_write_b128 v100, v[44:47]
	s_waitcnt vmcnt(6)
	ds_write_b128 v150, v[48:51]
	s_waitcnt vmcnt(5)
	ds_write_b128 v102, v[52:55]
	s_waitcnt vmcnt(4)
	ds_write_b128 v151, v[56:59]
	s_waitcnt vmcnt(3)
	ds_write_b128 v104, v[60:63]
	s_waitcnt vmcnt(2)
	ds_write_b128 v152, v[64:67]
	s_waitcnt vmcnt(1)
	ds_write_b128 v106, v[72:75]
	s_waitcnt vmcnt(0)
	ds_write_b128 v153, v[76:79]
	v_lshl_or_b32 v1, s22, 6, v111
	v_or_b32_e32 v144, s2, v1
	v_lshlrev_b64 v[140:141], 11, v[144:145]
	v_lshl_add_u64 v[88:89], v[142:143], 0, v[140:141]
	s_waitcnt lgkmcnt(0)
	s_barrier
	global_load_dwordx4 v[20:23], v[88:89], off
	global_load_dwordx4 v[24:27], v[88:89], off offset:64
	global_load_dword v194, v98, s[20:21] offset:868
	global_load_dword v195, v99, s[20:21] offset:868
	global_load_dword v196, v97, s[20:21] offset:868
	global_load_dword v197, v95, s[20:21] offset:868
	global_load_dword v198, v93, s[20:21] offset:868
	global_load_dword v199, v96, s[20:21] offset:868
	global_load_dword v200, v97, s[20:21] offset:992
	global_load_dword v201, v93, s[20:21] offset:992
	global_load_dword v202, v92, s[20:21] offset:868
	global_load_dword v203, v95, s[20:21] offset:992
	global_load_dword v204, v98, s[20:21] offset:992
	global_load_dword v205, v94, s[20:21] offset:868
	global_load_dword v206, v92, s[20:21] offset:992
	global_load_dword v207, v99, s[20:21] offset:1116
	global_load_dword v208, v96, s[20:21] offset:1116
	global_load_dword v209, v98, s[20:21] offset:1116
	global_load_dword v210, v94, s[20:21] offset:1116
	global_load_dword v211, v97, s[20:21] offset:1116
	global_load_dword v212, v93, s[20:21] offset:1116
	global_load_dword v213, v96, s[20:21] offset:992
	global_load_dword v226, v95, s[20:21] offset:1116
	global_load_dword v227, v92, s[20:21] offset:1116
	global_load_dword v228, v94, s[20:21] offset:992
	global_load_dword v229, v99, s[20:21] offset:1240
	global_load_dword v230, v96, s[20:21] offset:1240
	global_load_dword v231, v98, s[20:21] offset:1240
	global_load_dword v232, v94, s[20:21] offset:1240
	global_load_dword v233, v99, s[20:21] offset:992
	global_load_dword v234, v97, s[20:21] offset:1240
	global_load_dword v235, v93, s[20:21] offset:1240
	global_load_dword v236, v95, s[20:21] offset:1240
	global_load_dword v237, v92, s[20:21] offset:1240
	v_mad_u32_u24 v4, v0, s59, v117
	ds_read_b128 v[0:3], v4
	ds_read_b128 v[4:7], v4 offset:64
	s_waitcnt vmcnt(33) lgkmcnt(1)
	v_mfma_f32_16x16x32_bf16 v[0:3], v[0:3], v[20:23], 0
	s_waitcnt vmcnt(32) lgkmcnt(0)
	v_mfma_f32_16x16x32_bf16 v[28:31], v[4:7], v[24:27], v[0:3]
	s_nop 5
	v_or_b32_e32 v0, s35, v119
	v_mad_u32_u24 v4, v0, s59, v117
	ds_read_b128 v[0:3], v4
	ds_read_b128 v[4:7], v4 offset:64
	s_waitcnt lgkmcnt(1)
	v_mfma_f32_16x16x32_bf16 v[0:3], v[0:3], v[20:23], 0
	s_waitcnt lgkmcnt(0)
	v_mfma_f32_16x16x32_bf16 v[32:35], v[4:7], v[24:27], v[0:3]
	s_nop 5
	v_add_u32_e32 v0, s34, v115
	v_mad_u32_u24 v4, v0, s59, v117
	ds_read_b128 v[0:3], v4
	ds_read_b128 v[4:7], v4 offset:64
	s_waitcnt lgkmcnt(1)
	v_mfma_f32_16x16x32_bf16 v[0:3], v[0:3], v[20:23], 0
	s_waitcnt lgkmcnt(0)
	v_mfma_f32_16x16x32_bf16 v[36:39], v[4:7], v[24:27], v[0:3]
	s_nop 5
	v_add_u32_e32 v0, s34, v119
	v_mad_u32_u24 v4, v0, s59, v117
	ds_read_b128 v[0:3], v4
	ds_read_b128 v[4:7], v4 offset:64
	s_waitcnt lgkmcnt(1)
	v_mfma_f32_16x16x32_bf16 v[0:3], v[0:3], v[20:23], 0
	s_waitcnt lgkmcnt(0)
	v_mfma_f32_16x16x32_bf16 v[16:19], v[4:7], v[24:27], v[0:3]
	s_nop 5
	v_or_b32_e32 v0, s33, v115
	v_mad_u32_u24 v4, v0, s59, v117
	ds_read_b128 v[0:3], v4
	ds_read_b128 v[4:7], v4 offset:64
	s_waitcnt lgkmcnt(1)
	v_mfma_f32_16x16x32_bf16 v[0:3], v[0:3], v[20:23], 0
	s_waitcnt lgkmcnt(0)
	v_mfma_f32_16x16x32_bf16 v[12:15], v[4:7], v[24:27], v[0:3]
	s_nop 5
	v_add_u32_e32 v0, s33, v119
	v_mad_u32_u24 v4, v0, s59, v117
	ds_read_b128 v[0:3], v4
	ds_read_b128 v[4:7], v4 offset:64
	s_waitcnt lgkmcnt(1)
	v_mfma_f32_16x16x32_bf16 v[0:3], v[0:3], v[20:23], 0
	s_waitcnt lgkmcnt(0)
	v_mfma_f32_16x16x32_bf16 v[8:11], v[4:7], v[24:27], v[0:3]
	s_nop 5
	v_add_u32_e32 v0, s26, v115
	v_mad_u32_u24 v4, v0, s59, v117
	ds_read_b128 v[0:3], v4
	ds_read_b128 v[4:7], v4 offset:64
	s_waitcnt lgkmcnt(1)
	v_mfma_f32_16x16x32_bf16 v[0:3], v[0:3], v[20:23], 0
	s_waitcnt lgkmcnt(0)
	v_mfma_f32_16x16x32_bf16 v[4:7], v[4:7], v[24:27], v[0:3]
	s_nop 5
	v_add_u32_e32 v0, s26, v119
	v_mad_u32_u24 v40, v0, s59, v117
	ds_read_b128 v[0:3], v40
	ds_read_b128 v[40:43], v40 offset:64
	s_waitcnt lgkmcnt(1)
	v_mfma_f32_16x16x32_bf16 v[0:3], v[0:3], v[20:23], 0
	s_waitcnt lgkmcnt(0)
	v_mfma_f32_16x16x32_bf16 v[0:3], v[40:43], v[24:27], v[0:3]
	s_waitcnt vmcnt(0)
	v_fmamk_f32 v24, v196, 0x3fb8aa3b, v32
	v_cndmask_b32_e64 v24, v220, v24, s[46:47]
	v_fmamk_f32 v16, v200, 0x3fb8aa3b, v16
	v_fmamk_f32 v26, v197, 0x3fb8aa3b, v34
	v_cndmask_b32_e64 v27, v220, v26, s[50:51]
	v_cndmask_b32_e64 v16, v220, v16, s[46:47]
	v_fmamk_f32 v17, v201, 0x3fb8aa3b, v17
	v_fmamk_f32 v22, v194, 0x3fb8aa3b, v30
	v_cndmask_b32_e64 v23, v220, v22, s[42:43]
	v_cndmask_b32_e64 v17, v220, v17, s[48:49]
	v_fmamk_f32 v18, v203, 0x3fb8aa3b, v18
	v_cndmask_b32_e64 v32, v220, v18, s[50:51]
	v_fmac_f32_e32 v35, 0x3fb8aa3b, v202
	v_fmamk_f32 v25, v198, 0x3fb8aa3b, v33
	v_cndmask_b32_e64 v26, v220, v35, s[52:53]
	v_cndmask_b32_e64 v25, v220, v25, s[48:49]
	v_max_f32_e32 v33, v27, v26
	v_max3_f32 v33, v24, v25, v33
	v_fmac_f32_e32 v19, 0x3fb8aa3b, v206
	v_cndmask_b32_e64 v18, v220, v19, s[52:53]
	v_max_f32_e32 v34, v32, v18
	v_max3_f32 v34, v16, v17, v34
	v_fmamk_f32 v12, v207, 0x3fb8aa3b, v12
	v_cndmask_b32_e64 v12, v220, v12, s[38:39]
	v_fmamk_f32 v13, v208, 0x3fb8aa3b, v13
	v_cndmask_b32_e64 v13, v220, v13, s[40:41]
	v_fmamk_f32 v14, v209, 0x3fb8aa3b, v14
	v_cndmask_b32_e64 v19, v220, v14, s[42:43]
	v_fmamk_f32 v30, v204, 0x3fb8aa3b, v38
	v_fmac_f32_e32 v15, 0x3fb8aa3b, v210
	v_cndmask_b32_e64 v14, v220, v15, s[44:45]
	v_fmamk_f32 v8, v211, 0x3fb8aa3b, v8
	v_fmamk_f32 v21, v199, 0x3fb8aa3b, v29
	v_cndmask_b32_e64 v21, v220, v21, s[40:41]
	v_cndmask_b32_e64 v8, v220, v8, s[46:47]
	v_fmamk_f32 v9, v212, 0x3fb8aa3b, v9
	v_cndmask_b32_e64 v9, v220, v9, s[48:49]
	v_fmamk_f32 v10, v226, 0x3fb8aa3b, v10
	v_cndmask_b32_e64 v15, v220, v10, s[50:51]
	v_fmac_f32_e32 v31, 0x3fb8aa3b, v205
	v_cndmask_b32_e64 v22, v220, v31, s[44:45]
	v_cndmask_b32_e64 v31, v220, v30, s[42:43]
	v_fmac_f32_e32 v11, 0x3fb8aa3b, v227
	v_cndmask_b32_e64 v10, v220, v11, s[52:53]
	v_fmamk_f32 v4, v229, 0x3fb8aa3b, v4
	v_cndmask_b32_e64 v4, v220, v4, s[38:39]
	v_fmamk_f32 v5, v230, 0x3fb8aa3b, v5
	v_cndmask_b32_e64 v5, v220, v5, s[40:41]
	v_fmamk_f32 v6, v231, 0x3fb8aa3b, v6
	v_fmamk_f32 v20, v195, 0x3fb8aa3b, v28
	v_cndmask_b32_e64 v20, v220, v20, s[38:39]
	v_cndmask_b32_e64 v6, v220, v6, s[42:43]
	v_fmac_f32_e32 v7, 0x3fb8aa3b, v232
	v_cndmask_b32_e64 v7, v220, v7, s[44:45]
	v_fmamk_f32 v0, v234, 0x3fb8aa3b, v0
	v_fmamk_f32 v29, v213, 0x3fb8aa3b, v37
	v_cndmask_b32_e64 v29, v220, v29, s[40:41]
	v_cndmask_b32_e64 v0, v220, v0, s[46:47]
	v_fmamk_f32 v1, v235, 0x3fb8aa3b, v1
	v_fmamk_f32 v28, v233, 0x3fb8aa3b, v36
	v_cndmask_b32_e64 v28, v220, v28, s[38:39]
	v_cndmask_b32_e64 v1, v220, v1, s[48:49]
	v_fmamk_f32 v2, v236, 0x3fb8aa3b, v2
	v_fmac_f32_e32 v39, 0x3fb8aa3b, v228
	v_cndmask_b32_e64 v30, v220, v39, s[44:45]
	s_mov_b32 s20, 0xf149f2ca
	v_cndmask_b32_e64 v2, v220, v2, s[50:51]
	v_fmac_f32_e32 v3, 0x3fb8aa3b, v237
	v_max_f32_e32 v11, v23, v22
	v_max3_f32 v11, v20, v21, v11
	v_max3_f32 v11, v11, s20, v33
	v_max_f32_e32 v33, v31, v30
	v_max3_f32 v33, v28, v29, v33
	v_max3_f32 v11, v11, v33, v34
	v_max_f32_e32 v33, v19, v14
	v_max_f32_e32 v34, v15, v10
	v_cndmask_b32_e64 v3, v220, v3, s[52:53]
	v_max3_f32 v33, v12, v13, v33
	v_max3_f32 v34, v8, v9, v34
	v_max3_f32 v11, v11, v33, v34
	v_max_f32_e32 v33, v6, v7
	v_max_f32_e32 v34, v2, v3
	v_max3_f32 v33, v4, v5, v33
	v_max3_f32 v34, v0, v1, v34
	v_max3_f32 v11, v11, v33, v34
	v_and_b32_e32 v34, 64, v219
	v_xor_b32_e32 v33, 16, v219
	v_add_u32_e32 v34, 64, v34
	v_cmp_lt_i32_e32 vcc, v33, v34
	s_nop 1
	v_cndmask_b32_e32 v33, v219, v33, vcc
	v_lshlrev_b32_e32 v145, 2, v33
	ds_bpermute_b32 v33, v145, v11
	s_waitcnt lgkmcnt(0)
	v_max_f32_e32 v33, v33, v33
	v_max_f32_e32 v11, v11, v33
	v_xor_b32_e32 v33, 32, v219
	v_cmp_lt_i32_e32 vcc, v33, v34
	s_nop 1
	v_cndmask_b32_e32 v33, v219, v33, vcc
	v_lshlrev_b32_e32 v149, 2, v33
	ds_bpermute_b32 v33, v149, v11
	s_waitcnt lgkmcnt(0)
	v_max3_f32 v146, v11, v33, s20
	v_sub_f32_e32 v20, v20, v146
	v_exp_f32_e32 v33, v20
	v_sub_f32_e32 v21, v21, v146
	v_exp_f32_e32 v34, v21
	v_sub_f32_e32 v21, v23, v146
	v_exp_f32_e32 v35, v21
	v_sub_f32_e32 v21, v22, v146
	v_exp_f32_e32 v36, v21
	v_sub_f32_e32 v21, v24, v146
	v_add_f32_e32 v20, 0, v33
	v_exp_f32_e32 v24, v21
	v_sub_f32_e32 v21, v25, v146
	v_add_f32_e32 v20, v34, v20
	v_exp_f32_e32 v25, v21
	v_sub_f32_e32 v21, v27, v146
	v_add_f32_e32 v20, v35, v20
	v_exp_f32_e32 v27, v21
	v_sub_f32_e32 v21, v26, v146
	v_add_f32_e32 v20, v36, v20
	v_exp_f32_e32 v26, v21
	v_sub_f32_e32 v21, v28, v146
	v_add_f32_e32 v20, v24, v20
	v_exp_f32_e32 v28, v21
	v_sub_f32_e32 v21, v29, v146
	v_add_f32_e32 v20, v25, v20
	v_exp_f32_e32 v29, v21
	v_sub_f32_e32 v21, v31, v146
	v_add_f32_e32 v20, v27, v20
	v_exp_f32_e32 v31, v21
	v_sub_f32_e32 v21, v30, v146
	v_add_f32_e32 v20, v26, v20
	v_exp_f32_e32 v30, v21
	v_sub_f32_e32 v16, v16, v146
	v_add_f32_e32 v20, v28, v20
	v_exp_f32_e32 v37, v16
	v_sub_f32_e32 v17, v17, v146
	v_add_f32_e32 v20, v29, v20
	v_exp_f32_e32 v38, v17
	v_sub_f32_e32 v17, v32, v146
	v_add_f32_e32 v20, v31, v20
	v_exp_f32_e32 v32, v17
	v_sub_f32_e32 v17, v18, v146
	v_add_f32_e32 v20, v30, v20
	v_exp_f32_e32 v39, v17
	v_sub_f32_e32 v12, v12, v146
	v_add_f32_e32 v16, v37, v20
	v_exp_f32_e32 v40, v12
	v_sub_f32_e32 v13, v13, v146
	v_add_f32_e32 v16, v38, v16
	v_exp_f32_e32 v41, v13
	v_sub_f32_e32 v13, v19, v146
	v_add_f32_e32 v16, v32, v16
	v_exp_f32_e32 v42, v13
	v_sub_f32_e32 v13, v14, v146
	v_add_f32_e32 v16, v39, v16
	v_exp_f32_e32 v43, v13
	v_sub_f32_e32 v8, v8, v146
	v_add_f32_e32 v12, v40, v16
	v_exp_f32_e32 v44, v8
	v_sub_f32_e32 v9, v9, v146
	v_add_f32_e32 v12, v41, v12
	v_exp_f32_e32 v45, v9
	v_sub_f32_e32 v9, v15, v146
	v_add_f32_e32 v12, v42, v12
	v_exp_f32_e32 v46, v9
	v_sub_f32_e32 v9, v10, v146
	v_add_f32_e32 v12, v43, v12
	v_exp_f32_e32 v47, v9
	v_sub_f32_e32 v4, v4, v146
	v_add_f32_e32 v8, v44, v12
	v_exp_f32_e32 v48, v4
	v_sub_f32_e32 v5, v5, v146
	v_add_f32_e32 v8, v45, v8
	v_exp_f32_e32 v49, v5
	v_sub_f32_e32 v5, v6, v146
	v_add_f32_e32 v8, v46, v8
	v_exp_f32_e32 v50, v5
	v_sub_f32_e32 v5, v7, v146
	v_add_f32_e32 v8, v47, v8
	v_exp_f32_e32 v51, v5
	v_sub_f32_e32 v0, v0, v146
	v_add_f32_e32 v4, v48, v8
	v_exp_f32_e32 v52, v0
	v_sub_f32_e32 v1, v1, v146
	v_add_f32_e32 v4, v49, v4
	v_exp_f32_e32 v53, v1
	v_sub_f32_e32 v1, v2, v146
	v_add_f32_e32 v4, v50, v4
	v_exp_f32_e32 v54, v1
	v_sub_f32_e32 v1, v3, v146
	v_add_f32_e32 v4, v51, v4
	v_exp_f32_e32 v55, v1
	v_add_f32_e32 v0, v52, v4
	v_add_f32_e32 v0, v53, v0
	v_add_f32_e32 v0, v54, v0
	v_add_f32_e32 v0, v55, v0
	v_sub_f32_e32 v11, 0xf149f2ca, v146
	ds_bpermute_b32 v2, v145, v0
	v_exp_f32_e32 v1, v11
	s_or_b32 s20, s35, s60
	v_lshl_add_u32 v16, s20, 1, v121
	v_add_u32_e32 v12, v16, v123
	s_waitcnt lgkmcnt(0)
	v_add_f32_e32 v90, v0, v2
	v_mul_f32_e32 v20, 0, v1
	v_cvt_pk_bf16_f32 v0, v33, v34
	v_cvt_pk_bf16_f32 v1, v35, v36
	v_cvt_pk_bf16_f32 v2, v24, v25
	v_cvt_pk_bf16_f32 v3, v27, v26
	ds_read2_b64 v[4:7], v12 offset1:4
	v_add_u32_e32 v8, 0x4000, v12
	v_add_u32_e32 v12, 0x8000, v12
	v_add_u32_e32 v16, v16, v125
	ds_read2_b64 v[8:11], v8 offset0:32 offset1:36
	ds_read2_b64 v[12:15], v12 offset0:64 offset1:68
	ds_read2_b64 v[16:19], v16 offset1:4
	v_mov_b32_e32 v21, v20
	v_mov_b32_e32 v22, v20
	v_mov_b32_e32 v23, v20
	s_or_b32 s20, s34, s60
	ds_bpermute_b32 v91, v149, v90
	s_waitcnt lgkmcnt(4)
	v_mfma_f32_16x16x32_bf16 v[4:7], v[4:7], v[0:3], v[20:23]
	s_waitcnt lgkmcnt(3)
	v_mfma_f32_16x16x32_bf16 v[8:11], v[8:11], v[0:3], v[20:23]
	s_waitcnt lgkmcnt(2)
	v_mfma_f32_16x16x32_bf16 v[12:15], v[12:15], v[0:3], v[20:23]
	s_waitcnt lgkmcnt(1)
	v_mfma_f32_16x16x32_bf16 v[0:3], v[16:19], v[0:3], v[20:23]
	v_cvt_pk_bf16_f32 v16, v28, v29
	v_cvt_pk_bf16_f32 v17, v31, v30
	v_cvt_pk_bf16_f32 v18, v37, v38
	v_cvt_pk_bf16_f32 v19, v32, v39
	s_nop 2
	v_lshl_add_u32 v21, s20, 1, v121
	v_add_u32_e32 v26, v21, v123
	ds_read2_b64 v[22:25], v26 offset1:4
	s_waitcnt lgkmcnt(0)
	v_mfma_f32_16x16x32_bf16 v[4:7], v[22:25], v[16:19], v[4:7]
	v_add_u32_e32 v22, 0x4000, v26
	ds_read2_b64 v[22:25], v22 offset0:32 offset1:36
	v_add_u32_e32 v21, v21, v125
	s_waitcnt lgkmcnt(0)
	v_mfma_f32_16x16x32_bf16 v[8:11], v[22:25], v[16:19], v[8:11]
	v_add_u32_e32 v22, 0x8000, v26
	ds_read2_b64 v[22:25], v22 offset0:64 offset1:68
	s_or_b32 s20, s33, s60
	s_waitcnt lgkmcnt(0)
	v_mfma_f32_16x16x32_bf16 v[12:15], v[22:25], v[16:19], v[12:15]
	ds_read2_b64 v[22:25], v21 offset1:4
	v_lshl_add_u32 v21, s20, 1, v121
	v_add_u32_e32 v26, v21, v123
	s_waitcnt lgkmcnt(0)
	v_mfma_f32_16x16x32_bf16 v[0:3], v[22:25], v[16:19], v[0:3]
	v_cvt_pk_bf16_f32 v16, v40, v41
	v_cvt_pk_bf16_f32 v17, v42, v43
	v_cvt_pk_bf16_f32 v18, v44, v45
	v_cvt_pk_bf16_f32 v19, v46, v47
	ds_read2_b64 v[22:25], v26 offset1:4
	s_waitcnt lgkmcnt(0)
	v_mfma_f32_16x16x32_bf16 v[4:7], v[22:25], v[16:19], v[4:7]
	v_add_u32_e32 v22, 0x4000, v26
	ds_read2_b64 v[22:25], v22 offset0:32 offset1:36
	v_add_u32_e32 v21, v21, v125
	s_waitcnt lgkmcnt(0)
	v_mfma_f32_16x16x32_bf16 v[8:11], v[22:25], v[16:19], v[8:11]
	v_add_u32_e32 v22, 0x8000, v26
	ds_read2_b64 v[22:25], v22 offset0:64 offset1:68
	s_or_b32 s20, s26, s60
	s_waitcnt lgkmcnt(0)
	v_mfma_f32_16x16x32_bf16 v[12:15], v[22:25], v[16:19], v[12:15]
	ds_read2_b64 v[22:25], v21 offset1:4
	v_lshl_add_u32 v21, s20, 1, v121
	v_add_u32_e32 v26, v21, v123
	s_waitcnt lgkmcnt(0)
	v_mfma_f32_16x16x32_bf16 v[0:3], v[22:25], v[16:19], v[0:3]
	v_cvt_pk_bf16_f32 v16, v48, v49
	v_cvt_pk_bf16_f32 v17, v50, v51
	v_cvt_pk_bf16_f32 v18, v52, v53
	v_cvt_pk_bf16_f32 v19, v54, v55
	ds_read2_b64 v[22:25], v26 offset1:4
	s_waitcnt lgkmcnt(0)
	v_mfma_f32_16x16x32_bf16 v[4:7], v[22:25], v[16:19], v[4:7]
	v_add_u32_e32 v22, 0x4000, v26
	ds_read2_b64 v[22:25], v22 offset0:32 offset1:36
	v_add_u32_e32 v21, v21, v125
	s_waitcnt lgkmcnt(0)
	v_mfma_f32_16x16x32_bf16 v[8:11], v[22:25], v[16:19], v[8:11]
	v_add_u32_e32 v22, 0x8000, v26
	ds_read2_b64 v[22:25], v22 offset0:64 offset1:68
	s_or_b32 s20, s22, 1
	s_waitcnt lgkmcnt(0)
	v_mfma_f32_16x16x32_bf16 v[12:15], v[22:25], v[16:19], v[12:15]
	ds_read2_b64 v[22:25], v21 offset1:4
	s_waitcnt lgkmcnt(0)
	v_mfma_f32_16x16x32_bf16 v[16:19], v[22:25], v[16:19], v[0:3]
	s_nop 2
	v_sub_u32_e64 v0, s20, 4 clamp
	s_nop 0
	v_readfirstlane_b32 s21, v0
	s_min_u32 s21, s21, 8
	v_sub_u32_e64 v0, s20, 5 clamp
	v_cmp_ne_u32_e32 vcc, s21, v0
	v_lshl_or_b32 v0, s20, 6, v111
	v_or_b32_e32 v0, s2, v0
	v_mov_b32_e32 v1, s3
	v_lshlrev_b64 v[0:1], 11, v[0:1]
	v_lshl_add_u64 v[22:23], v[142:143], 0, v[0:1]
	global_load_dwordx4 v[0:3], v[22:23], off
	global_load_dwordx4 v[50:53], v[22:23], off offset:64
	s_cbranch_vccz .LBB0_120

	s_lshl_b32 s26, s21, 6
	s_add_i32 s33, s26, 0x1c0
	v_add_u32_e32 v194, s33, v108
	v_ashrrev_i32_e32 v195, 31, v194
	v_lshlrev_b64 v[194:195], 11, v[194:195]
	s_lshl_b32 s26, s21, 7
	v_lshl_add_u64 v[194:195], v[70:71], 0, v[194:195]
	v_lshl_add_u64 v[198:199], v[68:69], 0, s[26:27]
	s_barrier
	global_load_dwordx4 v[194:197], v[194:195], off
	s_nop 0
	global_load_dwordx4 v[198:201], v[198:199], off offset:896
	s_and_b32 s26, s33, 0x1c0
	v_add_u32_e32 v202, s26, v108
	v_mad_u64_u32 v[204:205], s[34:35], v202, s59, v[110:111]
	v_lshl_add_u32 v206, s26, 1, v109
	s_waitcnt vmcnt(1)
	ds_write_b128 v204, v[194:197]
	s_waitcnt vmcnt(0)
	ds_write_b128 v206, v[198:201]
	s_waitcnt lgkmcnt(0)
	s_barrier
.LBB0_120:
	s_add_i32 s21, s21, s61
	s_sub_i32 s20, s21, s20
	s_lshl_b32 s21, s21, 6
	s_and_b32 s35, s21, 0x1c0
	v_add_u32_e32 v21, s35, v115
	v_mad_u32_u24 v21, v21, s59, v117
	ds_read_b128 v[22:25], v21
	ds_read_b128 v[26:29], v21 offset:64
	v_add_u32_e32 v21, s35, v119
	v_mad_u32_u24 v21, v21, s59, v117
	s_add_i32 s26, s21, 64
	s_and_b32 s34, s26, 0x1c0
	s_and_b32 s33, s21, 0x140
	s_bitset1_b32 s33, 7
	s_addk_i32 s21, 0xc0
	s_and_b32 s26, s21, 0x1c0
	s_mul_i32 s20, s20, 31
	s_ashr_i32 s21, s20, 31
	s_lshl_b64 s[20:21], s[20:21], 2
	s_add_u32 s20, s36, s20
	s_addc_u32 s21, s23, s21
	global_load_dword v194, v99, s[20:21] offset:868
	global_load_dword v195, v96, s[20:21] offset:868
	global_load_dword v196, v98, s[20:21] offset:868
	global_load_dword v197, v94, s[20:21] offset:868
	global_load_dword v198, v97, s[20:21] offset:868
	global_load_dword v199, v93, s[20:21] offset:868
	global_load_dword v200, v95, s[20:21] offset:868
	global_load_dword v201, v92, s[20:21] offset:868
	global_load_dword v202, v99, s[20:21] offset:992
	global_load_dword v203, v96, s[20:21] offset:992
	global_load_dword v204, v98, s[20:21] offset:992
	global_load_dword v205, v94, s[20:21] offset:992
	global_load_dword v206, v97, s[20:21] offset:992
	global_load_dword v207, v93, s[20:21] offset:992
	global_load_dword v208, v95, s[20:21] offset:992
	global_load_dword v209, v92, s[20:21] offset:992
	global_load_dword v210, v99, s[20:21] offset:1116
	global_load_dword v211, v96, s[20:21] offset:1116
	global_load_dword v212, v98, s[20:21] offset:1116
	global_load_dword v213, v94, s[20:21] offset:1116
	global_load_dword v226, v97, s[20:21] offset:1116
	global_load_dword v227, v93, s[20:21] offset:1116
	global_load_dword v228, v95, s[20:21] offset:1116
	global_load_dword v229, v92, s[20:21] offset:1116
	global_load_dword v230, v99, s[20:21] offset:1240
	global_load_dword v231, v96, s[20:21] offset:1240
	global_load_dword v232, v98, s[20:21] offset:1240
	global_load_dword v233, v97, s[20:21] offset:1240
	global_load_dword v234, v93, s[20:21] offset:1240
	global_load_dword v235, v94, s[20:21] offset:1240
	global_load_dword v236, v95, s[20:21] offset:1240
	global_load_dword v237, v92, s[20:21] offset:1240
	s_waitcnt vmcnt(33) lgkmcnt(1)
	v_mfma_f32_16x16x32_bf16 v[22:25], v[22:25], v[0:3], 0
	s_waitcnt vmcnt(32) lgkmcnt(0)
	v_mfma_f32_16x16x32_bf16 v[46:49], v[26:29], v[50:53], v[22:25]
	s_nop 5
	ds_read_b128 v[22:25], v21
	ds_read_b128 v[26:29], v21 offset:64
	v_add_u32_e32 v21, s34, v115
	s_waitcnt lgkmcnt(1)
	v_mfma_f32_16x16x32_bf16 v[22:25], v[22:25], v[0:3], 0
	v_mad_u32_u24 v21, v21, s59, v117
	s_waitcnt lgkmcnt(0)
	v_mfma_f32_16x16x32_bf16 v[38:41], v[26:29], v[50:53], v[22:25]
	s_nop 4
	ds_read_b128 v[22:25], v21
	ds_read_b128 v[26:29], v21 offset:64
	v_add_u32_e32 v21, s34, v119
	v_mad_u32_u24 v21, v21, s59, v117
	s_waitcnt lgkmcnt(1)
	v_mfma_f32_16x16x32_bf16 v[22:25], v[22:25], v[0:3], 0
	s_waitcnt lgkmcnt(0)
	v_mfma_f32_16x16x32_bf16 v[42:45], v[26:29], v[50:53], v[22:25]
	s_nop 5
	ds_read_b128 v[22:25], v21
	ds_read_b128 v[26:29], v21 offset:64
	v_add_u32_e32 v21, s33, v115
	s_waitcnt lgkmcnt(1)
	v_mfma_f32_16x16x32_bf16 v[22:25], v[22:25], v[0:3], 0
	v_mad_u32_u24 v21, v21, s59, v117
	s_waitcnt lgkmcnt(0)
	v_mfma_f32_16x16x32_bf16 v[30:33], v[26:29], v[50:53], v[22:25]
	s_nop 4
	ds_read_b128 v[22:25], v21
	ds_read_b128 v[26:29], v21 offset:64
	v_add_u32_e32 v21, s33, v119
	v_mad_u32_u24 v21, v21, s59, v117
	s_waitcnt lgkmcnt(1)
	v_mfma_f32_16x16x32_bf16 v[22:25], v[22:25], v[0:3], 0
	s_waitcnt lgkmcnt(0)
	v_mfma_f32_16x16x32_bf16 v[34:37], v[26:29], v[50:53], v[22:25]
	s_nop 5
	ds_read_b128 v[22:25], v21
	ds_read_b128 v[26:29], v21 offset:64
	v_add_u32_e32 v21, s26, v115
	s_waitcnt lgkmcnt(1)
	v_mfma_f32_16x16x32_bf16 v[22:25], v[22:25], v[0:3], 0
	v_mad_u32_u24 v21, v21, s59, v117
	s_waitcnt lgkmcnt(0)
	v_mfma_f32_16x16x32_bf16 v[22:25], v[26:29], v[50:53], v[22:25]
	ds_read_b128 v[26:29], v21
	ds_read_b128 v[54:57], v21 offset:64
	v_add_u32_e32 v21, s26, v119
	v_mad_u32_u24 v21, v21, s59, v117
	s_waitcnt lgkmcnt(1)
	v_mfma_f32_16x16x32_bf16 v[26:29], v[26:29], v[0:3], 0
	s_waitcnt lgkmcnt(0)
	v_mfma_f32_16x16x32_bf16 v[26:29], v[54:57], v[50:53], v[26:29]
	ds_read_b128 v[54:57], v21
	ds_read_b128 v[58:61], v21 offset:64
	s_waitcnt lgkmcnt(1)
	v_mfma_f32_16x16x32_bf16 v[0:3], v[54:57], v[0:3], 0
	s_waitcnt vmcnt(0)
	v_fmamk_f32 v21, v194, 0x3fb8aa3b, v46
	s_waitcnt lgkmcnt(0)
	v_mfma_f32_16x16x32_bf16 v[0:3], v[58:61], v[50:53], v[0:3]
	v_cndmask_b32_e64 v21, v220, v21, s[38:39]
	v_fmamk_f32 v46, v195, 0x3fb8aa3b, v47
	v_cndmask_b32_e64 v46, v220, v46, s[40:41]
	v_fmamk_f32 v47, v196, 0x3fb8aa3b, v48
	v_cndmask_b32_e64 v48, v220, v47, s[42:43]
	v_fmac_f32_e32 v49, 0x3fb8aa3b, v197
	v_cndmask_b32_e64 v47, v220, v49, s[44:45]
	v_fmamk_f32 v38, v198, 0x3fb8aa3b, v38
	v_cndmask_b32_e64 v38, v220, v38, s[46:47]
	v_fmamk_f32 v39, v199, 0x3fb8aa3b, v39
	v_cndmask_b32_e64 v39, v220, v39, s[48:49]
	v_fmamk_f32 v40, v200, 0x3fb8aa3b, v40
	v_cndmask_b32_e64 v49, v220, v40, s[50:51]
	v_fmac_f32_e32 v41, 0x3fb8aa3b, v201
	v_cndmask_b32_e64 v40, v220, v41, s[52:53]
	v_fmamk_f32 v41, v202, 0x3fb8aa3b, v42
	v_cndmask_b32_e64 v41, v220, v41, s[38:39]
	v_fmamk_f32 v42, v203, 0x3fb8aa3b, v43
	v_cndmask_b32_e64 v42, v220, v42, s[40:41]
	v_fmamk_f32 v43, v204, 0x3fb8aa3b, v44
	v_cndmask_b32_e64 v44, v220, v43, s[42:43]
	v_fmac_f32_e32 v45, 0x3fb8aa3b, v205
	v_cndmask_b32_e64 v43, v220, v45, s[44:45]
	v_fmamk_f32 v30, v206, 0x3fb8aa3b, v30
	v_cndmask_b32_e64 v30, v220, v30, s[46:47]
	v_fmamk_f32 v31, v207, 0x3fb8aa3b, v31
	v_cndmask_b32_e64 v31, v220, v31, s[48:49]
	v_fmamk_f32 v32, v208, 0x3fb8aa3b, v32
	v_cndmask_b32_e64 v45, v220, v32, s[50:51]
	v_fmac_f32_e32 v33, 0x3fb8aa3b, v209
	v_cndmask_b32_e64 v32, v220, v33, s[52:53]
	v_max_f32_e32 v51, v45, v32
	v_max3_f32 v51, v30, v31, v51
	v_fmamk_f32 v33, v210, 0x3fb8aa3b, v34
	v_cndmask_b32_e64 v33, v220, v33, s[38:39]
	v_fmamk_f32 v34, v211, 0x3fb8aa3b, v35
	v_cndmask_b32_e64 v34, v220, v34, s[40:41]
	v_fmamk_f32 v35, v212, 0x3fb8aa3b, v36
	v_cndmask_b32_e64 v36, v220, v35, s[42:43]
	v_fmac_f32_e32 v37, 0x3fb8aa3b, v213
	v_cndmask_b32_e64 v35, v220, v37, s[44:45]
	v_fmamk_f32 v22, v226, 0x3fb8aa3b, v22
	v_cndmask_b32_e64 v22, v220, v22, s[46:47]
	v_fmamk_f32 v23, v227, 0x3fb8aa3b, v23
	v_cndmask_b32_e64 v37, v220, v23, s[48:49]
	v_fmamk_f32 v23, v228, 0x3fb8aa3b, v24
	v_cndmask_b32_e64 v50, v220, v23, s[50:51]
	v_fmac_f32_e32 v25, 0x3fb8aa3b, v229
	v_cndmask_b32_e64 v24, v220, v25, s[52:53]
	v_fmamk_f32 v23, v230, 0x3fb8aa3b, v26
	v_cndmask_b32_e64 v23, v220, v23, s[38:39]
	v_fmamk_f32 v26, v232, 0x3fb8aa3b, v28
	v_cndmask_b32_e64 v26, v220, v26, s[42:43]
	v_fmamk_f32 v0, v233, 0x3fb8aa3b, v0
	v_fmamk_f32 v25, v231, 0x3fb8aa3b, v27
	v_cndmask_b32_e64 v25, v220, v25, s[40:41]
	v_cndmask_b32_e64 v0, v220, v0, s[46:47]
	v_fmamk_f32 v1, v234, 0x3fb8aa3b, v1
	v_cndmask_b32_e64 v1, v220, v1, s[48:49]
	v_fmamk_f32 v2, v236, 0x3fb8aa3b, v2
	v_fmac_f32_e32 v29, 0x3fb8aa3b, v235
	v_cndmask_b32_e64 v27, v220, v29, s[44:45]
	v_max_f32_e32 v29, v49, v40
	v_max3_f32 v29, v38, v39, v29
	s_mov_b32 s20, 0xf149f2ca
	v_cndmask_b32_e64 v2, v220, v2, s[50:51]
	v_fmac_f32_e32 v3, 0x3fb8aa3b, v237
	v_max_f32_e32 v28, v48, v47
	v_max3_f32 v28, v21, v46, v28
	v_max3_f32 v28, v28, s20, v29
	v_max_f32_e32 v29, v44, v43
	v_max3_f32 v29, v41, v42, v29
	v_max3_f32 v28, v28, v29, v51
	v_max_f32_e32 v29, v36, v35
	v_max_f32_e32 v51, v50, v24
	v_cndmask_b32_e64 v3, v220, v3, s[52:53]
	v_max3_f32 v29, v33, v34, v29
	v_max3_f32 v51, v22, v37, v51
	v_max3_f32 v28, v28, v29, v51
	v_max_f32_e32 v29, v26, v27
	v_max_f32_e32 v51, v2, v3
	v_max3_f32 v29, v23, v25, v29
	v_max3_f32 v51, v0, v1, v51
	v_max3_f32 v28, v28, v29, v51
	ds_bpermute_b32 v29, v145, v28
	s_waitcnt lgkmcnt(0)
	v_max_f32_e32 v29, v29, v29
	v_max_f32_e32 v28, v28, v29
	ds_bpermute_b32 v29, v149, v28
	s_waitcnt lgkmcnt(0)
	v_max3_f32 v150, v28, v29, s20
	v_sub_f32_e32 v21, v21, v150
	v_exp_f32_e32 v29, v21
	v_sub_f32_e32 v46, v46, v150
	v_exp_f32_e32 v46, v46
	v_sub_f32_e32 v48, v48, v150
	v_exp_f32_e32 v48, v48
	v_sub_f32_e32 v47, v47, v150
	v_exp_f32_e32 v47, v47
	v_sub_f32_e32 v38, v38, v150
	v_add_f32_e32 v21, 0, v29
	v_exp_f32_e32 v38, v38
	v_sub_f32_e32 v39, v39, v150
	v_add_f32_e32 v21, v46, v21
	v_exp_f32_e32 v39, v39
	v_sub_f32_e32 v49, v49, v150
	v_add_f32_e32 v21, v48, v21
	v_exp_f32_e32 v49, v49
	v_sub_f32_e32 v40, v40, v150
	v_add_f32_e32 v21, v47, v21
	v_exp_f32_e32 v40, v40
	v_sub_f32_e32 v41, v41, v150
	v_add_f32_e32 v21, v38, v21
	v_exp_f32_e32 v41, v41
	v_sub_f32_e32 v42, v42, v150
	v_add_f32_e32 v21, v39, v21
	v_exp_f32_e32 v42, v42
	v_sub_f32_e32 v44, v44, v150
	v_add_f32_e32 v21, v49, v21
	v_exp_f32_e32 v44, v44
	v_sub_f32_e32 v43, v43, v150
	v_add_f32_e32 v21, v40, v21
	v_exp_f32_e32 v43, v43
	v_sub_f32_e32 v30, v30, v150
	v_add_f32_e32 v21, v41, v21
	v_exp_f32_e32 v51, v30
	v_sub_f32_e32 v30, v31, v150
	v_add_f32_e32 v21, v42, v21
	v_exp_f32_e32 v52, v30
	v_sub_f32_e32 v30, v45, v150
	v_add_f32_e32 v21, v44, v21
	v_exp_f32_e32 v45, v30
	v_sub_f32_e32 v30, v32, v150
	v_add_f32_e32 v21, v43, v21
	v_exp_f32_e32 v53, v30
	v_sub_f32_e32 v30, v33, v150
	v_add_f32_e32 v21, v51, v21
	v_exp_f32_e32 v54, v30
	v_sub_f32_e32 v30, v34, v150
	v_add_f32_e32 v21, v52, v21
	v_exp_f32_e32 v55, v30
	v_sub_f32_e32 v30, v36, v150
	v_add_f32_e32 v21, v45, v21
	v_exp_f32_e32 v56, v30
	v_sub_f32_e32 v30, v35, v150
	v_add_f32_e32 v21, v53, v21
	v_exp_f32_e32 v57, v30
	v_sub_f32_e32 v22, v22, v150
	v_add_f32_e32 v21, v54, v21
	v_exp_f32_e32 v62, v22
	v_sub_f32_e32 v22, v37, v150
	v_add_f32_e32 v21, v55, v21
	v_exp_f32_e32 v63, v22
	v_sub_f32_e32 v22, v50, v150
	v_add_f32_e32 v21, v56, v21
	v_exp_f32_e32 v50, v22
	v_sub_f32_e32 v22, v24, v150
	v_add_f32_e32 v21, v57, v21
	v_exp_f32_e32 v64, v22
	v_sub_f32_e32 v22, v23, v150
	v_add_f32_e32 v21, v62, v21
	v_exp_f32_e32 v65, v22
	v_sub_f32_e32 v22, v25, v150
	v_add_f32_e32 v21, v63, v21
	v_exp_f32_e32 v66, v22
	v_sub_f32_e32 v22, v26, v150
	v_add_f32_e32 v21, v50, v21
	v_exp_f32_e32 v67, v22
	v_sub_f32_e32 v22, v27, v150
	v_add_f32_e32 v21, v64, v21
	v_exp_f32_e32 v72, v22
	v_sub_f32_e32 v0, v0, v150
	v_add_f32_e32 v21, v65, v21
	v_exp_f32_e32 v73, v0
	v_sub_f32_e32 v1, v1, v150
	v_add_f32_e32 v21, v66, v21
	v_exp_f32_e32 v74, v1
	v_sub_f32_e32 v1, v2, v150
	v_add_f32_e32 v21, v67, v21
	v_exp_f32_e32 v75, v1
	v_sub_f32_e32 v1, v3, v150
	v_add_f32_e32 v21, v72, v21
	v_exp_f32_e32 v76, v1
	v_add_f32_e32 v0, v73, v21
	v_add_f32_e32 v0, v74, v0
	v_add_f32_e32 v0, v75, v0
	v_add_f32_e32 v0, v76, v0
	v_sub_f32_e32 v28, 0xf149f2ca, v150
	ds_bpermute_b32 v2, v145, v0
	v_exp_f32_e32 v1, v28
	s_or_b32 s20, s35, s60
	v_lshl_add_u32 v34, s20, 1, v121
	v_add_u32_e32 v30, v34, v123
	s_waitcnt lgkmcnt(0)
	v_add_f32_e32 v21, v0, v2
	v_mul_f32_e32 v58, 0, v1
	v_cvt_pk_bf16_f32 v0, v29, v46
	v_cvt_pk_bf16_f32 v1, v48, v47
	v_cvt_pk_bf16_f32 v2, v38, v39
	v_cvt_pk_bf16_f32 v3, v49, v40
	ds_read2_b64 v[22:25], v30 offset1:4
	v_add_u32_e32 v26, 0x4000, v30
	v_add_u32_e32 v30, 0x8000, v30
	v_add_u32_e32 v34, v34, v125
	ds_read2_b64 v[26:29], v26 offset0:32 offset1:36
	ds_read2_b64 v[30:33], v30 offset0:64 offset1:68
	ds_read2_b64 v[34:37], v34 offset1:4
	v_mov_b32_e32 v59, v58
	v_mov_b32_e32 v60, v58
	v_mov_b32_e32 v61, v58
	s_or_b32 s20, s34, s60
	ds_bpermute_b32 v100, v149, v21
	s_waitcnt lgkmcnt(4)
	v_mfma_f32_16x16x32_bf16 v[22:25], v[22:25], v[0:3], v[58:61]
	s_waitcnt lgkmcnt(3)
	v_mfma_f32_16x16x32_bf16 v[26:29], v[26:29], v[0:3], v[58:61]
	s_waitcnt lgkmcnt(2)
	v_mfma_f32_16x16x32_bf16 v[30:33], v[30:33], v[0:3], v[58:61]
	s_waitcnt lgkmcnt(1)
	v_mfma_f32_16x16x32_bf16 v[0:3], v[34:37], v[0:3], v[58:61]
	v_cvt_pk_bf16_f32 v34, v41, v42
	v_lshl_add_u32 v42, s20, 1, v121
	v_cvt_pk_bf16_f32 v35, v44, v43
	v_add_u32_e32 v43, v42, v123
	v_cvt_pk_bf16_f32 v36, v51, v52
	v_cvt_pk_bf16_f32 v37, v45, v53
	ds_read2_b64 v[38:41], v43 offset1:4
	s_waitcnt lgkmcnt(0)
	v_mfma_f32_16x16x32_bf16 v[22:25], v[38:41], v[34:37], v[22:25]
	v_add_u32_e32 v38, 0x4000, v43
	ds_read2_b64 v[38:41], v38 offset0:32 offset1:36
	s_or_b32 s20, s33, s60
	s_waitcnt lgkmcnt(0)
	v_mfma_f32_16x16x32_bf16 v[26:29], v[38:41], v[34:37], v[26:29]
	v_add_u32_e32 v38, 0x8000, v43
	ds_read2_b64 v[38:41], v38 offset0:64 offset1:68
	v_lshl_add_u32 v46, s20, 1, v121
	s_waitcnt lgkmcnt(0)
	v_mfma_f32_16x16x32_bf16 v[30:33], v[38:41], v[34:37], v[30:33]
	v_add_u32_e32 v38, v42, v125
	ds_read2_b64 v[38:41], v38 offset1:4
	v_add_u32_e32 v42, v46, v123
	s_waitcnt lgkmcnt(0)
	v_mfma_f32_16x16x32_bf16 v[0:3], v[38:41], v[34:37], v[0:3]
	v_cvt_pk_bf16_f32 v34, v54, v55
	v_cvt_pk_bf16_f32 v35, v56, v57
	v_cvt_pk_bf16_f32 v36, v62, v63
	v_cvt_pk_bf16_f32 v37, v50, v64
	ds_read2_b64 v[38:41], v42 offset1:4
	s_waitcnt lgkmcnt(0)
	v_mfma_f32_16x16x32_bf16 v[22:25], v[38:41], v[34:37], v[22:25]
	v_add_u32_e32 v38, 0x4000, v42
	ds_read2_b64 v[38:41], v38 offset0:32 offset1:36
	s_or_b32 s20, s26, s60
	s_waitcnt lgkmcnt(0)
	v_mfma_f32_16x16x32_bf16 v[38:41], v[38:41], v[34:37], v[26:29]
	s_nop 2
	v_add_u32_e32 v26, 0x8000, v42
	ds_read2_b64 v[26:29], v26 offset0:64 offset1:68
	v_lshl_add_u32 v50, s20, 1, v121
	s_waitcnt lgkmcnt(0)
	v_mfma_f32_16x16x32_bf16 v[42:45], v[26:29], v[34:37], v[30:33]
	v_add_u32_e32 v26, v46, v125
	ds_read2_b64 v[26:29], v26 offset1:4
	v_cvt_pk_bf16_f32 v46, v65, v66
	v_cvt_pk_bf16_f32 v47, v67, v72
	v_cvt_pk_bf16_f32 v48, v73, v74
	s_waitcnt lgkmcnt(0)
	v_mfma_f32_16x16x32_bf16 v[0:3], v[26:29], v[34:37], v[0:3]
	v_add_u32_e32 v34, v50, v123
	v_cvt_pk_bf16_f32 v49, v75, v76
	ds_read2_b64 v[26:29], v34 offset1:4
	s_waitcnt lgkmcnt(0)
	v_mfma_f32_16x16x32_bf16 v[26:29], v[26:29], v[46:49], v[22:25]
	s_nop 2
	v_add_u32_e32 v22, 0x4000, v34
	ds_read2_b64 v[22:25], v22 offset0:32 offset1:36
	s_or_b32 s20, s22, 2
	s_waitcnt lgkmcnt(0)
	v_mfma_f32_16x16x32_bf16 v[30:33], v[22:25], v[46:49], v[38:41]
	v_add_u32_e32 v22, 0x8000, v34
	ds_read2_b64 v[22:25], v22 offset0:64 offset1:68
	s_waitcnt lgkmcnt(0)
	v_mfma_f32_16x16x32_bf16 v[34:37], v[22:25], v[46:49], v[42:45]
	v_add_u32_e32 v22, v50, v125
	ds_read2_b64 v[22:25], v22 offset1:4
	s_waitcnt lgkmcnt(0)
	v_mfma_f32_16x16x32_bf16 v[38:41], v[22:25], v[46:49], v[0:3]
	s_nop 2
	v_sub_u32_e64 v0, s20, 4 clamp
	s_nop 0
	v_readfirstlane_b32 s21, v0
	v_sub_u32_e64 v0, s20, 5 clamp
	s_min_u32 s21, s21, 8
	v_min_u32_e32 v0, 8, v0
	v_cmp_eq_u32_e32 vcc, s21, v0
	v_lshl_or_b32 v0, s20, 6, v111
	v_or_b32_e32 v0, s2, v0
	v_mov_b32_e32 v1, s3
	v_lshlrev_b64 v[0:1], 11, v[0:1]
	v_lshl_add_u64 v[22:23], v[142:143], 0, v[0:1]
	global_load_dwordx4 v[0:3], v[22:23], off
	global_load_dwordx4 v[72:75], v[22:23], off offset:64
	s_cbranch_vccnz .LBB0_122

	s_lshl_b32 s26, s21, 6
	s_add_i32 s33, s26, 0x1c0
	v_add_u32_e32 v194, s33, v108
	v_ashrrev_i32_e32 v195, 31, v194
	v_lshlrev_b64 v[194:195], 11, v[194:195]
	s_lshl_b32 s26, s21, 7
	v_lshl_add_u64 v[194:195], v[70:71], 0, v[194:195]
	v_lshl_add_u64 v[198:199], v[68:69], 0, s[26:27]
	s_barrier
	global_load_dwordx4 v[194:197], v[194:195], off
	s_nop 0
	global_load_dwordx4 v[198:201], v[198:199], off offset:896
	s_and_b32 s26, s33, 0x1c0
	v_add_u32_e32 v204, s26, v108
	v_mad_u64_u32 v[204:205], s[34:35], v204, s59, v[110:111]
	v_lshl_add_u32 v206, s26, 1, v109
	s_waitcnt vmcnt(1)
	ds_write_b128 v204, v[194:197]
	s_waitcnt vmcnt(0)
	ds_write_b128 v206, v[198:201]
	s_waitcnt lgkmcnt(0)
	s_barrier
.LBB0_122:
	s_add_i32 s21, s21, s61
	s_sub_i32 s20, s21, s20
	s_lshl_b32 s21, s21, 6
	s_and_b32 s35, s21, 0x1c0
	v_add_u32_e32 v22, s35, v115
	v_mad_u32_u24 v42, v22, s59, v117
	ds_read_b128 v[22:25], v42
	ds_read_b128 v[42:45], v42 offset:64
	s_and_b32 s26, s21, 0x180
	s_or_b32 s34, s26, 64
	s_add_i32 s26, s21, 0x80
	s_and_b32 s33, s26, 0x1c0
	s_addk_i32 s21, 0xc0
	s_and_b32 s26, s21, 0x1c0
	s_mul_i32 s20, s20, 31
	s_ashr_i32 s21, s20, 31
	s_lshl_b64 s[20:21], s[20:21], 2
	s_add_u32 s20, s36, s20
	s_addc_u32 s21, s23, s21
	global_load_dword v194, v99, s[20:21] offset:868
	global_load_dword v195, v96, s[20:21] offset:868
	global_load_dword v196, v98, s[20:21] offset:868
	global_load_dword v197, v94, s[20:21] offset:868
	global_load_dword v198, v97, s[20:21] offset:868
	global_load_dword v199, v93, s[20:21] offset:868
	global_load_dword v200, v95, s[20:21] offset:868
	global_load_dword v201, v92, s[20:21] offset:868
	global_load_dword v202, v99, s[20:21] offset:992
	global_load_dword v203, v96, s[20:21] offset:992
	global_load_dword v204, v98, s[20:21] offset:992
	global_load_dword v205, v94, s[20:21] offset:992
	global_load_dword v206, v97, s[20:21] offset:992
	global_load_dword v207, v93, s[20:21] offset:992
	global_load_dword v208, v95, s[20:21] offset:992
	global_load_dword v209, v92, s[20:21] offset:992
	global_load_dword v210, v99, s[20:21] offset:1116
	global_load_dword v211, v96, s[20:21] offset:1116
	global_load_dword v212, v98, s[20:21] offset:1116
	global_load_dword v213, v94, s[20:21] offset:1116
	global_load_dword v226, v97, s[20:21] offset:1116
	global_load_dword v227, v93, s[20:21] offset:1116
	global_load_dword v228, v95, s[20:21] offset:1116
	global_load_dword v229, v92, s[20:21] offset:1116
	global_load_dword v230, v99, s[20:21] offset:1240
	global_load_dword v231, v96, s[20:21] offset:1240
	global_load_dword v232, v98, s[20:21] offset:1240
	global_load_dword v233, v97, s[20:21] offset:1240
	global_load_dword v234, v93, s[20:21] offset:1240
	global_load_dword v235, v94, s[20:21] offset:1240
	global_load_dword v236, v95, s[20:21] offset:1240
	global_load_dword v237, v92, s[20:21] offset:1240
	v_readlane_b32 s92, v252, 60
	s_mov_b64 s[90:91], s[0:1]
	v_readlane_b32 s93, v252, 61
	s_waitcnt vmcnt(33) lgkmcnt(1)
	v_mfma_f32_16x16x32_bf16 v[22:25], v[22:25], v[0:3], 0
	s_waitcnt vmcnt(32) lgkmcnt(0)
	v_mfma_f32_16x16x32_bf16 v[64:67], v[42:45], v[72:75], v[22:25]
	s_nop 5
	v_add_u32_e32 v22, s35, v119
	v_mad_u32_u24 v42, v22, s59, v117
	ds_read_b128 v[22:25], v42
	ds_read_b128 v[42:45], v42 offset:64
	s_waitcnt lgkmcnt(1)
	v_mfma_f32_16x16x32_bf16 v[22:25], v[22:25], v[0:3], 0
	s_waitcnt lgkmcnt(0)
	v_mfma_f32_16x16x32_bf16 v[54:57], v[42:45], v[72:75], v[22:25]
	s_nop 5
	v_add_u32_e32 v22, s34, v115
	v_mad_u32_u24 v42, v22, s59, v117
	ds_read_b128 v[22:25], v42
	ds_read_b128 v[42:45], v42 offset:64
	s_waitcnt lgkmcnt(1)
	v_mfma_f32_16x16x32_bf16 v[22:25], v[22:25], v[0:3], 0
	s_waitcnt lgkmcnt(0)
	v_mfma_f32_16x16x32_bf16 v[60:63], v[42:45], v[72:75], v[22:25]
	s_nop 5
	v_add_u32_e32 v22, s34, v119
	v_mad_u32_u24 v42, v22, s59, v117
	ds_read_b128 v[22:25], v42
	ds_read_b128 v[42:45], v42 offset:64
	s_waitcnt lgkmcnt(1)
	v_mfma_f32_16x16x32_bf16 v[22:25], v[22:25], v[0:3], 0
	s_waitcnt lgkmcnt(0)
	v_mfma_f32_16x16x32_bf16 v[46:49], v[42:45], v[72:75], v[22:25]
	s_nop 5
	v_add_u32_e32 v22, s33, v115
	v_mad_u32_u24 v42, v22, s59, v117
	ds_read_b128 v[22:25], v42
	ds_read_b128 v[42:45], v42 offset:64
	s_waitcnt lgkmcnt(1)
	v_mfma_f32_16x16x32_bf16 v[22:25], v[22:25], v[0:3], 0
	s_waitcnt lgkmcnt(0)
	v_mfma_f32_16x16x32_bf16 v[50:53], v[42:45], v[72:75], v[22:25]
	s_nop 5
	v_add_u32_e32 v22, s33, v119
	v_mad_u32_u24 v42, v22, s59, v117
	ds_read_b128 v[22:25], v42
	ds_read_b128 v[42:45], v42 offset:64
	s_waitcnt lgkmcnt(1)
	v_mfma_f32_16x16x32_bf16 v[22:25], v[22:25], v[0:3], 0
	s_waitcnt lgkmcnt(0)
	v_mfma_f32_16x16x32_bf16 v[22:25], v[42:45], v[72:75], v[22:25]
	v_add_u32_e32 v42, s26, v115
	v_mad_u32_u24 v59, v42, s59, v117
	ds_read_b128 v[42:45], v59
	ds_read_b128 v[76:79], v59 offset:64
	s_waitcnt lgkmcnt(1)
	v_mfma_f32_16x16x32_bf16 v[42:45], v[42:45], v[0:3], 0
	v_add_u32_e32 v59, s26, v119
	v_mad_u32_u24 v59, v59, s59, v117
	s_waitcnt lgkmcnt(0)
	v_mfma_f32_16x16x32_bf16 v[42:45], v[76:79], v[72:75], v[42:45]
	ds_read_b128 v[76:79], v59
	ds_read_b128 v[80:83], v59 offset:64
	s_waitcnt lgkmcnt(1)
	v_mfma_f32_16x16x32_bf16 v[0:3], v[76:79], v[0:3], 0
	s_waitcnt vmcnt(0)
	v_fmamk_f32 v59, v194, 0x3fb8aa3b, v64
	s_waitcnt lgkmcnt(0)
	v_mfma_f32_16x16x32_bf16 v[0:3], v[80:83], v[72:75], v[0:3]
	v_cndmask_b32_e64 v59, v220, v59, s[38:39]
	v_fmamk_f32 v64, v195, 0x3fb8aa3b, v65
	v_cndmask_b32_e64 v64, v220, v64, s[40:41]
	v_fmamk_f32 v65, v196, 0x3fb8aa3b, v66
	v_cndmask_b32_e64 v66, v220, v65, s[42:43]
	v_fmac_f32_e32 v67, 0x3fb8aa3b, v197
	v_cndmask_b32_e64 v65, v220, v67, s[44:45]
	v_fmamk_f32 v54, v198, 0x3fb8aa3b, v54
	v_cndmask_b32_e64 v54, v220, v54, s[46:47]
	v_fmamk_f32 v55, v199, 0x3fb8aa3b, v55
	v_cndmask_b32_e64 v55, v220, v55, s[48:49]
	v_fmamk_f32 v56, v200, 0x3fb8aa3b, v56
	v_cndmask_b32_e64 v67, v220, v56, s[50:51]
	v_fmac_f32_e32 v57, 0x3fb8aa3b, v201
	v_cndmask_b32_e64 v56, v220, v57, s[52:53]
	v_fmamk_f32 v57, v202, 0x3fb8aa3b, v60
	v_cndmask_b32_e64 v57, v220, v57, s[38:39]
	v_fmamk_f32 v60, v203, 0x3fb8aa3b, v61
	v_cndmask_b32_e64 v60, v220, v60, s[40:41]
	v_fmamk_f32 v61, v204, 0x3fb8aa3b, v62
	v_cndmask_b32_e64 v62, v220, v61, s[42:43]
	v_fmac_f32_e32 v63, 0x3fb8aa3b, v205
	v_cndmask_b32_e64 v61, v220, v63, s[44:45]
	v_fmamk_f32 v46, v206, 0x3fb8aa3b, v46
	v_cndmask_b32_e64 v46, v220, v46, s[46:47]
	v_fmamk_f32 v47, v207, 0x3fb8aa3b, v47
	v_cndmask_b32_e64 v47, v220, v47, s[48:49]
	v_fmamk_f32 v48, v208, 0x3fb8aa3b, v48
	v_cndmask_b32_e64 v63, v220, v48, s[50:51]
	v_fmac_f32_e32 v49, 0x3fb8aa3b, v209
	v_cndmask_b32_e64 v48, v220, v49, s[52:53]
	v_max_f32_e32 v73, v63, v48
	v_max3_f32 v73, v46, v47, v73
	v_fmamk_f32 v49, v210, 0x3fb8aa3b, v50
	v_cndmask_b32_e64 v49, v220, v49, s[38:39]
	v_fmamk_f32 v50, v211, 0x3fb8aa3b, v51
	v_cndmask_b32_e64 v50, v220, v50, s[40:41]
	v_fmamk_f32 v51, v212, 0x3fb8aa3b, v52
	v_cndmask_b32_e64 v52, v220, v51, s[42:43]
	v_fmac_f32_e32 v53, 0x3fb8aa3b, v213
	v_cndmask_b32_e64 v51, v220, v53, s[44:45]
	v_fmamk_f32 v22, v226, 0x3fb8aa3b, v22
	v_cndmask_b32_e64 v22, v220, v22, s[46:47]
	v_fmamk_f32 v23, v227, 0x3fb8aa3b, v23
	v_cndmask_b32_e64 v53, v220, v23, s[48:49]
	v_fmamk_f32 v23, v228, 0x3fb8aa3b, v24
	v_cndmask_b32_e64 v72, v220, v23, s[50:51]
	v_fmac_f32_e32 v25, 0x3fb8aa3b, v229
	v_cndmask_b32_e64 v24, v220, v25, s[52:53]
	v_fmamk_f32 v23, v230, 0x3fb8aa3b, v42
	v_cndmask_b32_e64 v23, v220, v23, s[38:39]
	v_fmamk_f32 v42, v232, 0x3fb8aa3b, v44
	v_cndmask_b32_e64 v42, v220, v42, s[42:43]
	v_fmamk_f32 v0, v233, 0x3fb8aa3b, v0
	v_fmamk_f32 v25, v231, 0x3fb8aa3b, v43
	v_cndmask_b32_e64 v25, v220, v25, s[40:41]
	v_cndmask_b32_e64 v0, v220, v0, s[46:47]
	v_fmamk_f32 v1, v234, 0x3fb8aa3b, v1
	v_cndmask_b32_e64 v1, v220, v1, s[48:49]
	v_fmamk_f32 v2, v236, 0x3fb8aa3b, v2
	v_fmac_f32_e32 v45, 0x3fb8aa3b, v235
	v_cndmask_b32_e64 v43, v220, v45, s[44:45]
	v_max_f32_e32 v45, v67, v56
	v_max3_f32 v45, v54, v55, v45
	s_mov_b32 s20, 0xf149f2ca
	v_cndmask_b32_e64 v2, v220, v2, s[50:51]
	v_fmac_f32_e32 v3, 0x3fb8aa3b, v237
	v_max_f32_e32 v44, v66, v65
	v_max3_f32 v44, v59, v64, v44
	v_max3_f32 v44, v44, s20, v45
	v_max_f32_e32 v45, v62, v61
	v_max3_f32 v45, v57, v60, v45
	v_max3_f32 v44, v44, v45, v73
	v_max_f32_e32 v45, v52, v51
	v_max_f32_e32 v73, v72, v24
	v_cndmask_b32_e64 v3, v220, v3, s[52:53]
	v_max3_f32 v45, v49, v50, v45
	v_max3_f32 v73, v22, v53, v73
	v_max3_f32 v44, v44, v45, v73
	v_max_f32_e32 v45, v42, v43
	v_max_f32_e32 v73, v2, v3
	v_max3_f32 v45, v23, v25, v45
	v_max3_f32 v73, v0, v1, v73
	v_max3_f32 v44, v44, v45, v73
	ds_bpermute_b32 v45, v145, v44
	s_waitcnt lgkmcnt(0)
	v_max_f32_e32 v45, v45, v45
	v_max_f32_e32 v44, v44, v45
	ds_bpermute_b32 v45, v149, v44
	s_waitcnt lgkmcnt(0)
	v_max3_f32 v153, v44, v45, s20
	v_sub_f32_e32 v45, v59, v153
	v_exp_f32_e32 v45, v45
	v_sub_f32_e32 v64, v64, v153
	v_exp_f32_e32 v64, v64
	v_sub_f32_e32 v66, v66, v153
	v_exp_f32_e32 v66, v66
	v_sub_f32_e32 v65, v65, v153
	v_exp_f32_e32 v65, v65
	v_sub_f32_e32 v54, v54, v153
	v_add_f32_e32 v59, 0, v45
	v_exp_f32_e32 v54, v54
	v_sub_f32_e32 v55, v55, v153
	v_add_f32_e32 v59, v64, v59
	v_exp_f32_e32 v55, v55
	v_sub_f32_e32 v67, v67, v153
	v_add_f32_e32 v59, v66, v59
	v_exp_f32_e32 v67, v67
	v_sub_f32_e32 v56, v56, v153
	v_add_f32_e32 v59, v65, v59
	v_exp_f32_e32 v56, v56
	v_sub_f32_e32 v57, v57, v153
	v_add_f32_e32 v59, v54, v59
	v_exp_f32_e32 v73, v57
	v_add_f32_e32 v59, v55, v59
	v_add_f32_e32 v59, v67, v59
	v_add_f32_e32 v59, v56, v59
	v_add_f32_e32 v57, v73, v59
	v_sub_f32_e32 v59, v60, v153
	v_exp_f32_e32 v59, v59
	v_sub_f32_e32 v60, v62, v153
	v_exp_f32_e32 v60, v60
	v_sub_f32_e32 v61, v61, v153
	v_exp_f32_e32 v61, v61
	v_sub_f32_e32 v46, v46, v153
	v_exp_f32_e32 v62, v46
	v_sub_f32_e32 v47, v47, v153
	v_add_f32_e32 v57, v59, v57
	v_exp_f32_e32 v74, v47
	v_sub_f32_e32 v47, v63, v153
	v_add_f32_e32 v57, v60, v57
	v_exp_f32_e32 v63, v47
	v_sub_f32_e32 v47, v48, v153
	v_add_f32_e32 v57, v61, v57
	v_exp_f32_e32 v75, v47
	v_sub_f32_e32 v47, v49, v153
	v_add_f32_e32 v46, v62, v57
	v_exp_f32_e32 v76, v47
	v_sub_f32_e32 v47, v50, v153
	v_add_f32_e32 v46, v74, v46
	v_exp_f32_e32 v77, v47
	v_sub_f32_e32 v47, v52, v153
	v_add_f32_e32 v46, v63, v46
	v_exp_f32_e32 v78, v47
	v_sub_f32_e32 v47, v51, v153
	v_add_f32_e32 v46, v75, v46
	v_exp_f32_e32 v79, v47
	v_sub_f32_e32 v22, v22, v153
	v_add_f32_e32 v46, v76, v46
	v_exp_f32_e32 v80, v22
	v_add_f32_e32 v46, v77, v46
	v_add_f32_e32 v46, v78, v46
	v_add_f32_e32 v46, v79, v46
	v_add_f32_e32 v22, v80, v46
	v_sub_f32_e32 v46, v53, v153
	v_exp_f32_e32 v81, v46
	v_sub_f32_e32 v46, v72, v153
	v_exp_f32_e32 v72, v46
	v_sub_f32_e32 v24, v24, v153
	v_exp_f32_e32 v82, v24
	v_sub_f32_e32 v23, v23, v153
	v_exp_f32_e32 v83, v23
	v_sub_f32_e32 v23, v25, v153
	v_add_f32_e32 v22, v81, v22
	v_exp_f32_e32 v84, v23
	v_sub_f32_e32 v23, v42, v153
	v_add_f32_e32 v22, v72, v22
	v_exp_f32_e32 v85, v23
	v_sub_f32_e32 v23, v43, v153
	v_add_f32_e32 v22, v82, v22
	v_exp_f32_e32 v86, v23
	v_sub_f32_e32 v0, v0, v153
	v_add_f32_e32 v22, v83, v22
	v_exp_f32_e32 v87, v0
	v_add_f32_e32 v22, v84, v22
	v_sub_f32_e32 v1, v1, v153
	v_add_f32_e32 v22, v85, v22
	v_exp_f32_e32 v101, v1
	v_sub_f32_e32 v1, v2, v153
	v_add_f32_e32 v22, v86, v22
	v_exp_f32_e32 v102, v1
	v_sub_f32_e32 v1, v3, v153
	s_or_b32 s20, s35, s60
	v_add_f32_e32 v0, v87, v22
	v_exp_f32_e32 v103, v1
	v_cvt_pk_bf16_f32 v22, v45, v64
	v_cvt_pk_bf16_f32 v23, v66, v65
	v_cvt_pk_bf16_f32 v24, v54, v55
	v_lshl_add_u32 v54, s20, 1, v121
	v_sub_f32_e32 v44, 0xf149f2ca, v153
	v_add_u32_e32 v50, v54, v123
	v_add_f32_e32 v0, v101, v0
	v_exp_f32_e32 v1, v44
	v_cvt_pk_bf16_f32 v25, v67, v56
	ds_read2_b64 v[42:45], v50 offset1:4
	v_add_u32_e32 v46, 0x4000, v50
	v_add_u32_e32 v50, 0x8000, v50
	v_add_u32_e32 v54, v54, v125
	v_add_f32_e32 v0, v102, v0
	ds_read2_b64 v[46:49], v46 offset0:32 offset1:36
	ds_read2_b64 v[50:53], v50 offset0:64 offset1:68
	ds_read2_b64 v[54:57], v54 offset1:4
	v_add_f32_e32 v0, v103, v0
	ds_bpermute_b32 v2, v145, v0
	s_or_b32 s20, s34, s60
	s_waitcnt lgkmcnt(0)
	v_add_f32_e32 v156, v0, v2
	v_mul_f32_e32 v0, 0, v1
	v_mov_b32_e32 v1, v0
	v_mov_b32_e32 v2, v0
	v_mov_b32_e32 v3, v0
	ds_bpermute_b32 v157, v149, v156
	s_nop 0
	v_mfma_f32_16x16x32_bf16 v[42:45], v[42:45], v[22:25], v[0:3]
	v_mfma_f32_16x16x32_bf16 v[46:49], v[46:49], v[22:25], v[0:3]
	v_mfma_f32_16x16x32_bf16 v[50:53], v[50:53], v[22:25], v[0:3]
	v_mfma_f32_16x16x32_bf16 v[22:25], v[54:57], v[22:25], v[0:3]
	v_cvt_pk_bf16_f32 v54, v73, v59
	v_cvt_pk_bf16_f32 v55, v60, v61
	v_cvt_pk_bf16_f32 v56, v62, v74
	v_cvt_pk_bf16_f32 v57, v63, v75
	s_nop 2
	v_lshl_add_u32 v1, s20, 1, v121
	v_add_u32_e32 v2, v1, v123
	ds_read2_b64 v[60:63], v2 offset1:4
	v_add_u32_e32 v3, 0x4000, v2
	s_waitcnt lgkmcnt(0)
	v_mfma_f32_16x16x32_bf16 v[42:45], v[60:63], v[54:57], v[42:45]
	ds_read2_b64 v[60:63], v3 offset0:32 offset1:36
	v_add_u32_e32 v2, 0x8000, v2
	v_add_u32_e32 v1, v1, v125
	s_waitcnt lgkmcnt(0)
	v_mfma_f32_16x16x32_bf16 v[46:49], v[60:63], v[54:57], v[46:49]
	ds_read2_b64 v[60:63], v2 offset0:64 offset1:68
	s_or_b32 s20, s33, s60
	s_waitcnt lgkmcnt(0)
	v_mfma_f32_16x16x32_bf16 v[50:53], v[60:63], v[54:57], v[50:53]
	ds_read2_b64 v[60:63], v1 offset1:4
	v_lshl_add_u32 v1, s20, 1, v121
	v_add_u32_e32 v2, v1, v123
	s_waitcnt lgkmcnt(0)
	v_mfma_f32_16x16x32_bf16 v[22:25], v[60:63], v[54:57], v[22:25]
	v_cvt_pk_bf16_f32 v54, v76, v77
	v_cvt_pk_bf16_f32 v55, v78, v79
	v_cvt_pk_bf16_f32 v56, v80, v81
	v_cvt_pk_bf16_f32 v57, v72, v82
	ds_read2_b64 v[60:63], v2 offset1:4
	v_add_u32_e32 v3, 0x4000, v2
	s_waitcnt lgkmcnt(0)
	v_mfma_f32_16x16x32_bf16 v[42:45], v[60:63], v[54:57], v[42:45]
	ds_read2_b64 v[60:63], v3 offset0:32 offset1:36
	v_add_u32_e32 v2, 0x8000, v2
	v_add_u32_e32 v1, v1, v125
	s_waitcnt lgkmcnt(0)
	v_mfma_f32_16x16x32_bf16 v[46:49], v[60:63], v[54:57], v[46:49]
	ds_read2_b64 v[60:63], v2 offset0:64 offset1:68
	s_or_b32 s20, s26, s60
	s_waitcnt lgkmcnt(0)
	v_mfma_f32_16x16x32_bf16 v[50:53], v[60:63], v[54:57], v[50:53]
	ds_read2_b64 v[60:63], v1 offset1:4
	v_lshl_add_u32 v1, s20, 1, v121
	v_add_u32_e32 v2, v1, v123
	s_waitcnt lgkmcnt(0)
	v_mfma_f32_16x16x32_bf16 v[22:25], v[60:63], v[54:57], v[22:25]
	v_cvt_pk_bf16_f32 v54, v83, v84
	v_cvt_pk_bf16_f32 v55, v85, v86
	v_cvt_pk_bf16_f32 v56, v87, v101
	v_cvt_pk_bf16_f32 v57, v102, v103
	ds_read2_b64 v[60:63], v2 offset1:4
	v_add_u32_e32 v3, 0x4000, v2
	s_waitcnt lgkmcnt(0)
	v_mfma_f32_16x16x32_bf16 v[42:45], v[60:63], v[54:57], v[42:45]
	ds_read2_b64 v[60:63], v3 offset0:32 offset1:36
	v_add_u32_e32 v2, 0x8000, v2
	v_add_u32_e32 v1, v1, v125
	s_waitcnt lgkmcnt(0)
	v_mfma_f32_16x16x32_bf16 v[46:49], v[60:63], v[54:57], v[46:49]
	ds_read2_b64 v[60:63], v2 offset0:64 offset1:68
	s_or_b32 s20, s22, 3
	s_waitcnt lgkmcnt(0)
	v_mfma_f32_16x16x32_bf16 v[50:53], v[60:63], v[54:57], v[50:53]
	ds_read2_b64 v[60:63], v1 offset1:4
	v_sub_u32_e64 v1, s20, 4 clamp
	s_waitcnt lgkmcnt(0)
	v_mfma_f32_16x16x32_bf16 v[54:57], v[60:63], v[54:57], v[22:25]
	v_readfirstlane_b32 s21, v1
	v_sub_u32_e64 v1, s20, 5 clamp
	s_min_u32 s21, s21, 8
	v_min_u32_e32 v1, 8, v1
	v_cmp_eq_u32_e32 vcc, s21, v1
	v_lshl_or_b32 v1, s20, 6, v111
	v_or_b32_e32 v2, s2, v1
	v_mov_b32_e32 v3, s3
	v_lshlrev_b64 v[2:3], 11, v[2:3]
	v_lshl_add_u64 v[2:3], v[142:143], 0, v[2:3]
	global_load_dwordx4 v[22:25], v[2:3], off
	global_load_dwordx4 v[102:105], v[2:3], off offset:64
	s_cbranch_vccnz .LBB0_124

	s_lshl_b32 s22, s21, 6
	s_addk_i32 s22, 0x1c0
	v_add_u32_e32 v198, s22, v108
	v_ashrrev_i32_e32 v199, 31, v198
	v_lshlrev_b64 v[198:199], 11, v[198:199]
	s_lshl_b32 s26, s21, 7
	v_lshl_add_u64 v[198:199], v[70:71], 0, v[198:199]
	v_lshl_add_u64 v[200:201], v[68:69], 0, s[26:27]
	s_barrier
	global_load_dwordx4 v[194:197], v[198:199], off
	s_nop 0
	global_load_dwordx4 v[200:203], v[200:201], off offset:896
	s_and_b32 s22, s22, 0x1c0
	v_add_u32_e32 v206, s22, v108
	v_mad_u64_u32 v[198:199], s[34:35], v206, s59, v[110:111]
	v_lshl_add_u32 v207, s22, 1, v109
	s_waitcnt vmcnt(1)
	ds_write_b128 v198, v[194:197]
	s_waitcnt vmcnt(0)
	ds_write_b128 v207, v[200:203]
	s_waitcnt lgkmcnt(0)
	s_barrier
.LBB0_124:
	s_add_i32 s21, s21, s61
	s_lshl_b32 s2, s21, 6
	s_and_b32 s33, s2, 0x1c0
	v_add_u32_e32 v1, s33, v115
	v_mad_u32_u24 v1, v1, s59, v117
	ds_read_b128 v[60:63], v1
	ds_read_b128 v[64:67], v1 offset:64
	v_add_u32_e32 v1, s33, v119
	v_mad_u32_u24 v1, v1, s59, v117
	s_sub_i32 s20, s21, s20
	s_add_i32 s21, s2, 64
	s_and_b32 s26, s21, 0x1c0
	s_add_i32 s21, s2, 0x80
	s_and_b32 s22, s21, 0x1c0
	s_addk_i32 s2, 0xc0
	s_and_b32 s2, s2, 0x1c0
	s_mul_i32 s20, s20, 31
	s_ashr_i32 s21, s20, 31
	s_lshl_b64 s[20:21], s[20:21], 2
	s_add_u32 s20, s36, s20
	s_addc_u32 s21, s23, s21
	global_load_dword v194, v99, s[20:21] offset:868
	global_load_dword v195, v98, s[20:21] offset:868
	global_load_dword v196, v96, s[20:21] offset:868
	global_load_dword v197, v97, s[20:21] offset:868
	global_load_dword v198, v93, s[20:21] offset:868
	global_load_dword v199, v94, s[20:21] offset:868
	global_load_dword v200, v95, s[20:21] offset:868
	global_load_dword v201, v92, s[20:21] offset:868
	global_load_dword v202, v99, s[20:21] offset:992
	global_load_dword v203, v96, s[20:21] offset:992
	global_load_dword v204, v98, s[20:21] offset:992
	global_load_dword v205, v94, s[20:21] offset:992
	global_load_dword v206, v97, s[20:21] offset:992
	global_load_dword v207, v93, s[20:21] offset:992
	global_load_dword v208, v95, s[20:21] offset:992
	global_load_dword v209, v92, s[20:21] offset:992
	global_load_dword v210, v99, s[20:21] offset:1116
	global_load_dword v211, v96, s[20:21] offset:1116
	global_load_dword v212, v98, s[20:21] offset:1116
	global_load_dword v213, v94, s[20:21] offset:1116
	global_load_dword v226, v97, s[20:21] offset:1116
	global_load_dword v227, v93, s[20:21] offset:1116
	global_load_dword v228, v95, s[20:21] offset:1116
	global_load_dword v229, v92, s[20:21] offset:1116
	global_load_dword v230, v99, s[20:21] offset:1240
	global_load_dword v231, v96, s[20:21] offset:1240
	global_load_dword v232, v98, s[20:21] offset:1240
	global_load_dword v233, v97, s[20:21] offset:1240
	global_load_dword v234, v93, s[20:21] offset:1240
	global_load_dword v235, v94, s[20:21] offset:1240
	global_load_dword v236, v95, s[20:21] offset:1240
	global_load_dword v237, v92, s[20:21] offset:1240
	v_readlane_b32 s0, v255, 10
	v_readlane_b32 s1, v255, 11
	s_waitcnt vmcnt(33) lgkmcnt(1)
	v_mfma_f32_16x16x32_bf16 v[60:63], v[60:63], v[22:25], 0
	s_waitcnt vmcnt(32) lgkmcnt(0)
	v_mfma_f32_16x16x32_bf16 v[84:87], v[64:67], v[102:105], v[60:63]
	s_nop 5
	ds_read_b128 v[60:63], v1
	ds_read_b128 v[64:67], v1 offset:64
	v_add_u32_e32 v1, s26, v115
	s_waitcnt lgkmcnt(1)
	v_mfma_f32_16x16x32_bf16 v[60:63], v[60:63], v[22:25], 0
	v_mad_u32_u24 v1, v1, s59, v117
	s_waitcnt lgkmcnt(0)
	v_mfma_f32_16x16x32_bf16 v[76:79], v[64:67], v[102:105], v[60:63]
	s_nop 4
	ds_read_b128 v[60:63], v1
	ds_read_b128 v[64:67], v1 offset:64
	v_add_u32_e32 v1, s26, v119
	v_mad_u32_u24 v1, v1, s59, v117
	s_waitcnt lgkmcnt(1)
	v_mfma_f32_16x16x32_bf16 v[60:63], v[60:63], v[22:25], 0
	s_waitcnt lgkmcnt(0)
	v_mfma_f32_16x16x32_bf16 v[80:83], v[64:67], v[102:105], v[60:63]
	s_nop 5
	ds_read_b128 v[60:63], v1
	ds_read_b128 v[64:67], v1 offset:64
	v_add_u32_e32 v1, s22, v115
	s_waitcnt lgkmcnt(1)
	v_mfma_f32_16x16x32_bf16 v[60:63], v[60:63], v[22:25], 0
	v_mad_u32_u24 v1, v1, s59, v117
	s_waitcnt lgkmcnt(0)
	v_mfma_f32_16x16x32_bf16 v[68:71], v[64:67], v[102:105], v[60:63]
	s_nop 4
	ds_read_b128 v[60:63], v1
	ds_read_b128 v[64:67], v1 offset:64
	v_add_u32_e32 v1, s22, v119
	v_mad_u32_u24 v1, v1, s59, v117
	s_waitcnt lgkmcnt(1)
	v_mfma_f32_16x16x32_bf16 v[60:63], v[60:63], v[22:25], 0
	s_waitcnt lgkmcnt(0)
	v_mfma_f32_16x16x32_bf16 v[72:75], v[64:67], v[102:105], v[60:63]
	s_nop 5
	ds_read_b128 v[60:63], v1
	ds_read_b128 v[64:67], v1 offset:64
	v_add_u32_e32 v1, s2, v115
	s_waitcnt lgkmcnt(1)
	v_mfma_f32_16x16x32_bf16 v[60:63], v[60:63], v[22:25], 0
	v_mad_u32_u24 v1, v1, s59, v117
	s_waitcnt lgkmcnt(0)
	v_mfma_f32_16x16x32_bf16 v[60:63], v[64:67], v[102:105], v[60:63]
	ds_read_b128 v[64:67], v1
	ds_read_b128 v[158:161], v1 offset:64
	v_add_u32_e32 v1, s2, v119
	v_mad_u32_u24 v1, v1, s59, v117
	s_waitcnt lgkmcnt(1)
	v_mfma_f32_16x16x32_bf16 v[64:67], v[64:67], v[22:25], 0
	s_or_b32 s2, s2, s60
	s_waitcnt lgkmcnt(0)
	v_mfma_f32_16x16x32_bf16 v[64:67], v[158:161], v[102:105], v[64:67]
	ds_read_b128 v[158:161], v1
	ds_read_b128 v[162:165], v1 offset:64
	s_waitcnt lgkmcnt(1)
	v_mfma_f32_16x16x32_bf16 v[22:25], v[158:161], v[22:25], 0
	s_waitcnt vmcnt(0)
	v_fmamk_f32 v1, v194, 0x3fb8aa3b, v84
	s_waitcnt lgkmcnt(0)
	v_mfma_f32_16x16x32_bf16 v[22:25], v[162:165], v[102:105], v[22:25]
	v_cndmask_b32_e64 v1, v220, v1, s[38:39]
	v_fmamk_f32 v76, v197, 0x3fb8aa3b, v76
	v_fmamk_f32 v3, v195, 0x3fb8aa3b, v86
	v_cndmask_b32_e64 v59, v220, v3, s[42:43]
	v_cndmask_b32_e64 v76, v220, v76, s[46:47]
	v_fmamk_f32 v77, v198, 0x3fb8aa3b, v77
	v_cndmask_b32_e64 v77, v220, v77, s[48:49]
	v_fmamk_f32 v78, v200, 0x3fb8aa3b, v78
	v_cndmask_b32_e64 v84, v220, v78, s[50:51]
	v_fmac_f32_e32 v87, 0x3fb8aa3b, v199
	v_cndmask_b32_e64 v3, v220, v87, s[44:45]
	v_fmac_f32_e32 v79, 0x3fb8aa3b, v201
	v_cndmask_b32_e64 v78, v220, v79, s[52:53]
	v_fmamk_f32 v79, v202, 0x3fb8aa3b, v80
	v_cndmask_b32_e64 v79, v220, v79, s[38:39]
	v_fmamk_f32 v80, v203, 0x3fb8aa3b, v81
	v_cndmask_b32_e64 v80, v220, v80, s[40:41]
	v_fmamk_f32 v81, v204, 0x3fb8aa3b, v82
	v_cndmask_b32_e64 v82, v220, v81, s[42:43]
	v_fmac_f32_e32 v83, 0x3fb8aa3b, v205
	v_cndmask_b32_e64 v81, v220, v83, s[44:45]
	v_fmamk_f32 v68, v206, 0x3fb8aa3b, v68
	v_cndmask_b32_e64 v68, v220, v68, s[46:47]
	v_fmamk_f32 v69, v207, 0x3fb8aa3b, v69
	v_cndmask_b32_e64 v69, v220, v69, s[48:49]
	v_fmamk_f32 v70, v208, 0x3fb8aa3b, v70
	v_cndmask_b32_e64 v83, v220, v70, s[50:51]
	v_fmamk_f32 v2, v196, 0x3fb8aa3b, v85
	v_cndmask_b32_e64 v2, v220, v2, s[40:41]
	v_fmac_f32_e32 v71, 0x3fb8aa3b, v209
	v_cndmask_b32_e64 v70, v220, v71, s[52:53]
	v_max_f32_e32 v86, v83, v70
	v_max3_f32 v86, v68, v69, v86
	v_fmamk_f32 v71, v210, 0x3fb8aa3b, v72
	v_cndmask_b32_e64 v71, v220, v71, s[38:39]
	v_fmamk_f32 v72, v211, 0x3fb8aa3b, v73
	v_cndmask_b32_e64 v72, v220, v72, s[40:41]
	v_fmamk_f32 v73, v212, 0x3fb8aa3b, v74
	v_cndmask_b32_e64 v74, v220, v73, s[42:43]
	v_fmac_f32_e32 v75, 0x3fb8aa3b, v213
	v_cndmask_b32_e64 v73, v220, v75, s[44:45]
	v_fmamk_f32 v60, v226, 0x3fb8aa3b, v60
	v_cndmask_b32_e64 v60, v220, v60, s[46:47]
	v_fmamk_f32 v61, v227, 0x3fb8aa3b, v61
	v_cndmask_b32_e64 v75, v220, v61, s[48:49]
	v_fmamk_f32 v61, v228, 0x3fb8aa3b, v62
	v_cndmask_b32_e64 v85, v220, v61, s[50:51]
	v_fmac_f32_e32 v63, 0x3fb8aa3b, v229
	v_cndmask_b32_e64 v62, v220, v63, s[52:53]
	v_fmamk_f32 v61, v230, 0x3fb8aa3b, v64
	v_cndmask_b32_e64 v61, v220, v61, s[38:39]
	v_fmamk_f32 v64, v232, 0x3fb8aa3b, v66
	v_cndmask_b32_e64 v64, v220, v64, s[42:43]
	v_fmamk_f32 v22, v233, 0x3fb8aa3b, v22
	v_fmamk_f32 v63, v231, 0x3fb8aa3b, v65
	v_cndmask_b32_e64 v63, v220, v63, s[40:41]
	v_cndmask_b32_e64 v22, v220, v22, s[46:47]
	v_fmamk_f32 v23, v234, 0x3fb8aa3b, v23
	v_cndmask_b32_e64 v23, v220, v23, s[48:49]
	v_fmamk_f32 v24, v236, 0x3fb8aa3b, v24
	v_fmac_f32_e32 v67, 0x3fb8aa3b, v235
	v_cndmask_b32_e64 v65, v220, v67, s[44:45]
	v_max_f32_e32 v67, v84, v78
	v_max3_f32 v67, v76, v77, v67
	s_mov_b32 s20, 0xf149f2ca
	v_cndmask_b32_e64 v24, v220, v24, s[50:51]
	v_fmac_f32_e32 v25, 0x3fb8aa3b, v237
	v_max_f32_e32 v66, v59, v3
	v_max3_f32 v66, v1, v2, v66
	v_max3_f32 v66, v66, s20, v67
	v_max_f32_e32 v67, v82, v81
	v_max3_f32 v67, v79, v80, v67
	v_max3_f32 v66, v66, v67, v86
	v_max_f32_e32 v67, v74, v73
	v_max_f32_e32 v86, v85, v62
	v_cndmask_b32_e64 v25, v220, v25, s[52:53]
	v_max3_f32 v67, v71, v72, v67
	v_max3_f32 v86, v60, v75, v86
	v_max3_f32 v66, v66, v67, v86
	v_max_f32_e32 v67, v64, v65
	v_max_f32_e32 v86, v24, v25
	v_max3_f32 v67, v61, v63, v67
	v_max3_f32 v86, v22, v23, v86
	v_max3_f32 v66, v66, v67, v86
	ds_bpermute_b32 v67, v145, v66
	s_waitcnt lgkmcnt(0)
	v_max_f32_e32 v67, v67, v67
	v_max_f32_e32 v66, v66, v67
	ds_bpermute_b32 v67, v149, v66
	s_waitcnt lgkmcnt(0)
	v_max3_f32 v159, v66, v67, s20
	v_sub_f32_e32 v1, v1, v159
	v_exp_f32_e32 v67, v1
	v_sub_f32_e32 v2, v2, v159
	v_exp_f32_e32 v2, v2
	v_sub_f32_e32 v59, v59, v159
	v_exp_f32_e32 v59, v59
	v_sub_f32_e32 v3, v3, v159
	v_exp_f32_e32 v3, v3
	v_sub_f32_e32 v76, v76, v159
	v_add_f32_e32 v1, 0, v67
	v_exp_f32_e32 v76, v76
	v_sub_f32_e32 v77, v77, v159
	v_add_f32_e32 v1, v2, v1
	v_exp_f32_e32 v77, v77
	v_sub_f32_e32 v84, v84, v159
	v_add_f32_e32 v1, v59, v1
	v_exp_f32_e32 v84, v84
	v_sub_f32_e32 v78, v78, v159
	v_add_f32_e32 v1, v3, v1
	v_exp_f32_e32 v78, v78
	v_sub_f32_e32 v79, v79, v159
	v_add_f32_e32 v1, v76, v1
	v_exp_f32_e32 v86, v79
	v_sub_f32_e32 v79, v80, v159
	v_add_f32_e32 v1, v77, v1
	v_exp_f32_e32 v80, v79
	v_sub_f32_e32 v79, v82, v159
	v_add_f32_e32 v1, v84, v1
	v_exp_f32_e32 v82, v79
	v_sub_f32_e32 v79, v81, v159
	v_add_f32_e32 v1, v78, v1
	v_exp_f32_e32 v81, v79
	v_sub_f32_e32 v68, v68, v159
	v_add_f32_e32 v1, v86, v1
	v_exp_f32_e32 v87, v68
	v_sub_f32_e32 v68, v69, v159
	v_add_f32_e32 v1, v80, v1
	v_exp_f32_e32 v92, v68
	v_sub_f32_e32 v68, v83, v159
	v_add_f32_e32 v1, v82, v1
	v_exp_f32_e32 v83, v68
	v_sub_f32_e32 v68, v70, v159
	v_add_f32_e32 v1, v81, v1
	v_exp_f32_e32 v93, v68
	v_sub_f32_e32 v68, v71, v159
	v_add_f32_e32 v1, v87, v1
	v_exp_f32_e32 v94, v68
	v_sub_f32_e32 v68, v72, v159
	v_add_f32_e32 v1, v92, v1
	v_exp_f32_e32 v95, v68
	v_sub_f32_e32 v68, v74, v159
	v_add_f32_e32 v1, v83, v1
	v_exp_f32_e32 v96, v68
	v_sub_f32_e32 v68, v73, v159
	v_add_f32_e32 v1, v93, v1
	v_exp_f32_e32 v97, v68
	v_sub_f32_e32 v60, v60, v159
	v_add_f32_e32 v1, v94, v1
	v_exp_f32_e32 v98, v60
	v_sub_f32_e32 v60, v75, v159
	v_add_f32_e32 v1, v95, v1
	v_exp_f32_e32 v99, v60
	v_sub_f32_e32 v60, v85, v159
	v_add_f32_e32 v1, v96, v1
	v_exp_f32_e32 v85, v60
	v_sub_f32_e32 v60, v62, v159
	v_add_f32_e32 v1, v97, v1
	v_exp_f32_e32 v101, v60
	v_sub_f32_e32 v60, v61, v159
	v_add_f32_e32 v1, v98, v1
	v_exp_f32_e32 v102, v60
	v_sub_f32_e32 v60, v63, v159
	v_add_f32_e32 v1, v99, v1
	v_exp_f32_e32 v103, v60
	v_sub_f32_e32 v60, v64, v159
	v_add_f32_e32 v1, v85, v1
	v_exp_f32_e32 v104, v60
	v_sub_f32_e32 v60, v65, v159
	v_add_f32_e32 v1, v101, v1
	v_exp_f32_e32 v105, v60
	v_sub_f32_e32 v22, v22, v159
	v_add_f32_e32 v1, v102, v1
	v_exp_f32_e32 v106, v22
	v_sub_f32_e32 v22, v23, v159
	v_add_f32_e32 v1, v103, v1
	v_exp_f32_e32 v107, v22
	v_sub_f32_e32 v22, v24, v159
	s_or_b32 s20, s33, s60
	v_add_f32_e32 v1, v104, v1
	v_exp_f32_e32 v147, v22
	v_sub_f32_e32 v22, v25, v159
	v_cvt_pk_bf16_f32 v60, v67, v2
	v_lshl_add_u32 v2, s20, 1, v121
	v_sub_f32_e32 v66, 0xf149f2ca, v159
	v_add_f32_e32 v1, v105, v1
	v_exp_f32_e32 v148, v22
	v_cvt_pk_bf16_f32 v61, v59, v3
	v_add_u32_e32 v3, v2, v123
	v_add_f32_e32 v1, v106, v1
	v_exp_f32_e32 v22, v66
	v_cvt_pk_bf16_f32 v62, v76, v77
	v_cvt_pk_bf16_f32 v63, v84, v78
	ds_read2_b64 v[64:67], v3 offset1:4
	v_add_u32_e32 v59, 0x4000, v3
	v_add_u32_e32 v3, 0x8000, v3
	v_add_u32_e32 v2, v2, v125
	v_add_f32_e32 v1, v107, v1
	ds_read2_b64 v[68:71], v59 offset0:32 offset1:36
	ds_read2_b64 v[72:75], v3 offset0:64 offset1:68
	ds_read2_b64 v[76:79], v2 offset1:4
	v_add_f32_e32 v1, v147, v1
	v_add_f32_e32 v1, v148, v1
	ds_bpermute_b32 v23, v145, v1
	s_or_b32 s20, s26, s60
	v_mul_f32_e32 v22, 0, v22
	v_lshl_add_u32 v2, s20, 1, v121
	v_mov_b32_e32 v24, v22
	s_waitcnt lgkmcnt(0)
	v_add_f32_e32 v1, v1, v23
	v_mov_b32_e32 v23, v22
	v_mov_b32_e32 v25, v22
	v_add_u32_e32 v3, v2, v123
	v_add_u32_e32 v2, v2, v125
	v_mfma_f32_16x16x32_bf16 v[64:67], v[64:67], v[60:63], v[22:25]
	s_or_b32 s20, s22, s60
	ds_bpermute_b32 v158, v149, v1
	v_mfma_f32_16x16x32_bf16 v[68:71], v[68:71], v[60:63], v[22:25]
	v_mfma_f32_16x16x32_bf16 v[72:75], v[72:75], v[60:63], v[22:25]
	v_mfma_f32_16x16x32_bf16 v[60:63], v[76:79], v[60:63], v[22:25]
	v_cvt_pk_bf16_f32 v76, v86, v80
	v_cvt_pk_bf16_f32 v77, v82, v81
	v_cvt_pk_bf16_f32 v78, v87, v92
	v_cvt_pk_bf16_f32 v79, v83, v93
	ds_read2_b64 v[80:83], v3 offset1:4
	s_nop 1
	v_add_u32_e32 v23, 0x4000, v3
	s_waitcnt lgkmcnt(0)
	v_mfma_f32_16x16x32_bf16 v[64:67], v[80:83], v[76:79], v[64:67]
	ds_read2_b64 v[80:83], v23 offset0:32 offset1:36
	v_add_u32_e32 v3, 0x8000, v3
	s_waitcnt lgkmcnt(0)
	v_mfma_f32_16x16x32_bf16 v[68:71], v[80:83], v[76:79], v[68:71]
	ds_read2_b64 v[80:83], v3 offset0:64 offset1:68
	s_waitcnt lgkmcnt(0)
	v_mfma_f32_16x16x32_bf16 v[72:75], v[80:83], v[76:79], v[72:75]
	ds_read2_b64 v[80:83], v2 offset1:4
	v_lshl_add_u32 v2, s20, 1, v121
	v_add_u32_e32 v3, v2, v123
	s_waitcnt lgkmcnt(0)
	v_mfma_f32_16x16x32_bf16 v[60:63], v[80:83], v[76:79], v[60:63]
	v_cvt_pk_bf16_f32 v76, v94, v95
	v_cvt_pk_bf16_f32 v77, v96, v97
	v_cvt_pk_bf16_f32 v78, v98, v99
	v_cvt_pk_bf16_f32 v79, v85, v101
	ds_read2_b64 v[80:83], v3 offset1:4
	v_add_u32_e32 v23, 0x4000, v3
	s_waitcnt lgkmcnt(0)
	v_mfma_f32_16x16x32_bf16 v[64:67], v[80:83], v[76:79], v[64:67]
	ds_read2_b64 v[80:83], v23 offset0:32 offset1:36
	v_add_u32_e32 v3, 0x8000, v3
	v_add_u32_e32 v2, v2, v125
	s_waitcnt lgkmcnt(0)
	v_mfma_f32_16x16x32_bf16 v[68:71], v[80:83], v[76:79], v[68:71]
	ds_read2_b64 v[80:83], v3 offset0:64 offset1:68
	s_waitcnt lgkmcnt(0)
	v_mfma_f32_16x16x32_bf16 v[72:75], v[80:83], v[76:79], v[72:75]
	ds_read2_b64 v[80:83], v2 offset1:4
	v_lshl_add_u32 v2, s2, 1, v121
	v_add_u32_e32 v3, v2, v123
	s_waitcnt lgkmcnt(0)
	v_mfma_f32_16x16x32_bf16 v[76:79], v[80:83], v[76:79], v[60:63]
	v_cvt_pk_bf16_f32 v80, v102, v103
	v_cvt_pk_bf16_f32 v81, v104, v105
	v_cvt_pk_bf16_f32 v82, v106, v107
	v_cvt_pk_bf16_f32 v83, v147, v148
	s_nop 2
	ds_read2_b64 v[60:63], v3 offset1:4
	v_add_u32_e32 v23, 0x4000, v3
	s_waitcnt lgkmcnt(0)
	v_mfma_f32_16x16x32_bf16 v[60:63], v[60:63], v[80:83], v[64:67]
	s_nop 2
	ds_read2_b64 v[64:67], v23 offset0:32 offset1:36
	v_add_u32_e32 v3, 0x8000, v3
	v_add_u32_e32 v2, v2, v125
	s_waitcnt lgkmcnt(0)
	v_mfma_f32_16x16x32_bf16 v[64:67], v[64:67], v[80:83], v[68:71]
	s_nop 2
	ds_read2_b64 v[68:71], v3 offset0:64 offset1:68
	s_waitcnt lgkmcnt(0)
	v_mfma_f32_16x16x32_bf16 v[68:71], v[68:71], v[80:83], v[72:75]
	s_nop 2
	ds_read2_b64 v[72:75], v2 offset1:4
	s_waitcnt lgkmcnt(0)
	v_mfma_f32_16x16x32_bf16 v[72:75], v[72:75], v[80:83], v[76:79]
	s_barrier
	s_and_saveexec_b64 s[20:21], s[0:1]
	s_xor_b64 s[20:21], exec, s[20:21]
	s_cbranch_execz .LBB0_130
	s_lshl_b64 s[22:23], s[56:57], 15
	v_lshl_add_u64 v[2:3], v[130:131], 0, s[22:23]
	s_movk_i32 s2, 0x90
	s_movk_i32 s26, 0x5ff
	v_mov_b32_e32 v23, v192
	v_ashrrev_i32_e32 v24, 3, v23
	v_ashrrev_i32_e32 v25, 31, v24
	v_lshlrev_b64 v[176:177], 7, v[24:25]
	v_lshl_add_u64 v[176:177], v[2:3], 0, v[176:177]
	global_load_dwordx4 v[76:79], v[176:177], off
	v_mad_u32_u24 v168, v24, s2, v110
	v_add_u32_e32 v23, 0x200, v192
	v_ashrrev_i32_e32 v24, 3, v23
	v_ashrrev_i32_e32 v25, 31, v24
	v_lshlrev_b64 v[176:177], 7, v[24:25]
	v_lshl_add_u64 v[176:177], v[2:3], 0, v[176:177]
	global_load_dwordx4 v[80:83], v[176:177], off
	v_mad_u32_u24 v169, v24, s2, v110
	v_add_u32_e32 v23, 0x400, v192
	v_ashrrev_i32_e32 v24, 3, v23
	v_ashrrev_i32_e32 v25, 31, v24
	v_lshlrev_b64 v[176:177], 7, v[24:25]
	v_lshl_add_u64 v[176:177], v[2:3], 0, v[176:177]
	global_load_dwordx4 v[84:87], v[176:177], off
	v_mad_u32_u24 v170, v24, s2, v110
	v_add_u32_e32 v23, 0x600, v192
	v_ashrrev_i32_e32 v24, 3, v23
	v_ashrrev_i32_e32 v25, 31, v24
	v_lshlrev_b64 v[176:177], 7, v[24:25]
	v_lshl_add_u64 v[176:177], v[2:3], 0, v[176:177]
	global_load_dwordx4 v[92:95], v[176:177], off
	v_mad_u32_u24 v171, v24, s2, v110
	v_lshl_add_u64 v[2:3], v[132:133], 0, s[22:23]
	s_movk_i32 s2, 0x210
	v_mov_b32_e32 v23, v192
	v_ashrrev_i32_e32 v24, 5, v23
	v_ashrrev_i32_e32 v25, 31, v24
	v_lshlrev_b64 v[176:177], 9, v[24:25]
	v_lshl_add_u64 v[176:177], v[2:3], 0, v[176:177]
	global_load_dwordx4 v[96:99], v[176:177], off
	v_mad_u32_u24 v172, v24, s2, v134
	v_add_u32_e32 v23, 0x200, v192
	v_ashrrev_i32_e32 v24, 5, v23
	v_ashrrev_i32_e32 v25, 31, v24
	v_lshlrev_b64 v[176:177], 9, v[24:25]
	v_lshl_add_u64 v[176:177], v[2:3], 0, v[176:177]
	global_load_dwordx4 v[104:107], v[176:177], off
	v_mad_u32_u24 v173, v24, s2, v134
	v_add_u32_e32 v23, 0x400, v192
	v_ashrrev_i32_e32 v24, 5, v23
	v_ashrrev_i32_e32 v25, 31, v24
	v_lshlrev_b64 v[176:177], 9, v[24:25]
	v_lshl_add_u64 v[176:177], v[2:3], 0, v[176:177]
	global_load_dwordx4 v[160:163], v[176:177], off
	v_mad_u32_u24 v174, v24, s2, v134
	v_add_u32_e32 v23, 0x600, v192
	v_ashrrev_i32_e32 v24, 5, v23
	v_ashrrev_i32_e32 v25, 31, v24
	v_lshlrev_b64 v[176:177], 9, v[24:25]
	v_lshl_add_u64 v[176:177], v[2:3], 0, v[176:177]
	global_load_dwordx4 v[164:167], v[176:177], off
	v_mad_u32_u24 v175, v24, s2, v134
	s_waitcnt vmcnt(7)
	ds_write_b128 v168, v[76:79]
	s_waitcnt vmcnt(6)
	ds_write_b128 v169, v[80:83]
	s_waitcnt vmcnt(5)
	ds_write_b128 v170, v[84:87]
	s_waitcnt vmcnt(4)
	ds_write_b128 v171, v[92:95]
	s_waitcnt vmcnt(3)
	ds_write_b128 v172, v[96:99]
	s_waitcnt vmcnt(2)
	ds_write_b128 v173, v[104:107]
	s_waitcnt vmcnt(1)
	ds_write_b128 v174, v[160:163]
	s_waitcnt vmcnt(0)
	ds_write_b128 v175, v[164:167]
